# chunk-MLP unit: v rows, u/gate tiles and Ws all requested at unit start (addresses recomputed up front), plus prepper wait move
# speedup vs baseline: 1.0029x; 1.0013x over previous
.LBB0_290:
	s_or_b64 exec, exec, s[0:1]
	s_add_i32 s0, 0, 0x23ff0
	s_cmp_lg_u32 s0, -1
	s_cselect_b32 s0, s0, 0
	s_cselect_b32 s1, s69, 0
	s_waitcnt vmcnt(0)
	v_mov_b32_e32 v0, s0
	v_mov_b32_e32 v1, s1
	s_waitcnt vmcnt(0) lgkmcnt(0)
	s_barrier
	flat_load_dword v4, v[0:1] sc0 sc1
	s_waitcnt vmcnt(0)
	s_movk_i32 s0, 0x710
	s_waitcnt lgkmcnt(0)
	v_cmp_gt_i32_e32 vcc, s0, v4
	s_mov_b64 s[0:1], -1
	s_and_saveexec_b64 s[94:95], vcc
	s_cbranch_execz .LBB0_285
	s_movk_i32 s0, 0x5f
	v_cmp_lt_i32_e32 vcc, s0, v4
	v_mov_b32_e32 v0, 1
	s_and_saveexec_b64 s[2:3], vcc
	s_movk_i32 s0, 0x510
	v_cmp_gt_u32_e64 s[0:1], s0, v4
	s_nop 1
	v_cndmask_b32_e64 v0, 16, 8, s[0:1]
	s_movk_i32 s0, 0x38f
	v_cmp_lt_u32_e64 s[0:1], s0, v4
	s_nop 1
	v_cndmask_b32_e64 v0, 4, v0, s[0:1]
	s_movk_i32 s0, 0x8f
	v_cmp_lt_u32_e64 s[0:1], s0, v4
	s_nop 1
	v_cndmask_b32_e64 v0, 2, v0, s[0:1]
	s_or_b64 exec, exec, s[2:3]
	v_and_b32_e32 v0, s86, v0
	v_cmp_ne_u32_e64 s[0:1], 0, v0
	s_and_saveexec_b64 s[2:3], s[0:1]
	s_xor_b64 s[96:97], exec, s[2:3]
	s_cbranch_execz .LBB0_483
	s_and_saveexec_b64 s[0:1], vcc
	s_xor_b64 s[0:1], exec, s[0:1]
	v_writelane_b32 v255, s0, 41
	s_nop 1
	v_writelane_b32 v255, s1, 42
	s_cbranch_execz .LBB0_440
	s_movk_i32 s0, 0x8f
	v_cmp_lt_u32_e32 vcc, s0, v4
	s_and_saveexec_b64 s[0:1], vcc
	s_xor_b64 s[0:1], exec, s[0:1]
	s_cbranch_execz .LBB0_388
	v_writelane_b32 v255, s0, 43
	s_nop 1
	v_writelane_b32 v255, s1, 44
	s_movk_i32 s0, 0x38f
	v_cmp_lt_u32_e32 vcc, s0, v4
	s_and_saveexec_b64 s[0:1], vcc
	s_xor_b64 s[78:79], exec, s[0:1]
	s_cbranch_execz .LBB0_345
	s_movk_i32 s0, 0x50f
	v_cmp_lt_u32_e32 vcc, s0, v4
	s_and_saveexec_b64 s[0:1], vcc
	s_xor_b64 s[0:1], exec, s[0:1]
	s_cbranch_execz .LBB0_305
	v_mov_b32_e32 v7, v238
	s_movk_i32 s2, 0x1000
	v_and_b32_e32 v5, 3, v4
	s_nop 0
	v_cmp_gt_i32_e32 vcc, s2, v7
	s_and_saveexec_b64 s[2:3], vcc
	s_movk_i32 s20, 0x110
	s_cbranch_execz .LBB0_301
	v_readlane_b32 s4, v254, 5
	v_lshlrev_b32_e32 v2, 16, v5
	v_readlane_b32 s5, v254, 6
	v_readlane_b32 s18, v254, 19
	v_readlane_b32 s19, v254, 20
	v_lshlrev_b32_e32 v6, 2, v7
	s_mov_b64 s[4:5], 0
	v_lshl_add_u64 v[0:1], s[18:19], 0, v[2:3]
	v_mov_b32_e32 v8, v7
	v_readlane_b32 s6, v254, 7
	v_readlane_b32 s7, v254, 8
	v_readlane_b32 s8, v254, 9
	v_readlane_b32 s9, v254, 10
	v_readlane_b32 s10, v254, 11
	v_readlane_b32 s11, v254, 12
	v_readlane_b32 s12, v254, 13
	v_readlane_b32 s13, v254, 14
	v_readlane_b32 s14, v254, 15
	v_readlane_b32 s15, v254, 16
	v_readlane_b32 s16, v254, 17
	v_readlane_b32 s17, v254, 18
	v_readlane_b32 s52, v255, 26
	v_readlane_b32 s53, v255, 27
	v_readlane_b32 s58, v254, 23
	v_readlane_b32 s59, v254, 24
	v_mov_b32_e32 v244, 0x7fff5e00
	v_lshl_add_u32 v244, v4, 5, v244
	v_and_b32_e32 v244, 0x7fffff80, v244
	v_ashrrev_i32_e32 v245, 6, v7
	v_add_u32_e32 v250, v245, v244
	v_lshlrev_b32_e32 v246, 8, v5
	v_mov_b32_e32 v247, 0
	v_mad_i64_i32 v[248:249], s[54:55], v250, s87, v[246:247]
	v_and_b32_e32 v251, 63, v7
	v_lshlrev_b32_e32 v250, 2, v251
	v_mov_b32_e32 v251, 0
	v_lshl_add_u64 v[248:249], v[248:249], 0, v[250:251]
	v_lshl_add_u64 v[248:249], s[52:53], 0, v[248:249]
	s_mov_b64 s[56:57], 0x1b900
	global_load_dword v210, v[248:249], off
	v_lshl_add_u64 v[248:249], v[248:249], 0, s[56:57]
	global_load_dword v211, v[248:249], off
	v_lshl_add_u64 v[248:249], v[248:249], 0, s[56:57]
	global_load_dword v212, v[248:249], off
	v_lshl_add_u64 v[248:249], v[248:249], 0, s[56:57]
	global_load_dword v213, v[248:249], off
	v_lshl_add_u64 v[248:249], v[248:249], 0, s[56:57]
	global_load_dword v214, v[248:249], off
	v_lshl_add_u64 v[248:249], v[248:249], 0, s[56:57]
	global_load_dword v215, v[248:249], off
	v_lshl_add_u64 v[248:249], v[248:249], 0, s[56:57]
	global_load_dword v216, v[248:249], off
	v_lshl_add_u64 v[248:249], v[248:249], 0, s[56:57]
	global_load_dword v217, v[248:249], off
	v_lshl_add_u64 v[248:249], v[248:249], 0, s[56:57]
	global_load_dword v218, v[248:249], off
	v_lshl_add_u64 v[248:249], v[248:249], 0, s[56:57]
	global_load_dword v219, v[248:249], off
	v_lshl_add_u64 v[248:249], v[248:249], 0, s[56:57]
	global_load_dword v220, v[248:249], off
	v_lshl_add_u64 v[248:249], v[248:249], 0, s[56:57]
	global_load_dword v221, v[248:249], off
	v_lshl_add_u64 v[248:249], v[248:249], 0, s[56:57]
	global_load_dword v222, v[248:249], off
	v_lshl_add_u64 v[248:249], v[248:249], 0, s[56:57]
	global_load_dword v223, v[248:249], off
	v_lshl_add_u64 v[248:249], v[248:249], 0, s[56:57]
	global_load_dword v224, v[248:249], off
	v_lshl_add_u64 v[248:249], v[248:249], 0, s[56:57]
	global_load_dword v225, v[248:249], off
	v_and_b32_e32 v248, 15, v7
	v_lshl_or_b32 v245, v245, 4, v248
	v_add_u32_e32 v244, v245, v244
	v_mov_b64_e32 v[250:251], s[58:59]
	v_mad_i64_i32 v[250:251], s[54:55], v244, s87, v[250:251]
	v_lshl_add_u64 v[250:251], v[250:251], 0, v[246:247]
	v_lshrrev_b32_e32 v246, 1, v7
	v_and_b32_e32 v246, 24, v246
	v_lshl_add_u64 v[250:251], v[250:251], 0, v[246:247]
	s_mov_b64 s[60:61], 0x1000
	v_lshl_add_u64 v[250:251], v[250:251], 0, s[60:61]
	global_load_dwordx2 v[126:127], v[250:251], off offset:2592
	global_load_dwordx2 v[142:143], v[250:251], off offset:544
	global_load_dwordx2 v[128:129], v[250:251], off offset:2624
	global_load_dwordx2 v[144:145], v[250:251], off offset:576
	global_load_dwordx2 v[130:131], v[250:251], off offset:2656
	global_load_dwordx2 v[146:147], v[250:251], off offset:608
	global_load_dwordx2 v[132:133], v[250:251], off offset:2688
	global_load_dwordx2 v[148:149], v[250:251], off offset:640
	global_load_dwordx2 v[134:135], v[250:251], off offset:2720
	global_load_dwordx2 v[244:245], v[250:251], off offset:672
	global_load_dwordx2 v[136:137], v[250:251], off offset:2752
	global_load_dwordx2 v[246:247], v[250:251], off offset:704
	global_load_dwordx2 v[138:139], v[250:251], off offset:2784
	global_load_dwordx2 v[248:249], v[250:251], off offset:736
	global_load_dwordx2 v[140:141], v[250:251], off offset:2816
	global_load_dwordx2 v[250:251], v[250:251], off offset:768
	v_ashrrev_i32_e32 v9, 5, v8
	v_lshlrev_b32_e32 v10, 7, v9
	v_and_b32_e32 v14, 0x7c, v6
	v_ashrrev_i32_e32 v11, 31, v10
	v_lshlrev_b32_e32 v2, 2, v14
	v_lshl_add_u64 v[10:11], v[10:11], 2, v[0:1]
	v_lshl_add_u64 v[10:11], v[10:11], 0, v[2:3]
	s_mov_b64 s[6:7], 0x2000
	global_load_dwordx4 v[178:181], v[10:11], off
	v_lshl_add_u64 v[10:11], v[10:11], 0, s[6:7]
	global_load_dwordx4 v[182:185], v[10:11], off
	v_lshl_add_u64 v[10:11], v[10:11], 0, s[6:7]
	global_load_dwordx4 v[186:189], v[10:11], off
	v_lshl_add_u64 v[10:11], v[10:11], 0, s[6:7]
	global_load_dwordx4 v[190:193], v[10:11], off
	v_lshl_add_u64 v[10:11], v[10:11], 0, s[6:7]
	global_load_dwordx4 v[194:197], v[10:11], off
	v_lshl_add_u64 v[10:11], v[10:11], 0, s[6:7]
	global_load_dwordx4 v[198:201], v[10:11], off
	v_lshl_add_u64 v[10:11], v[10:11], 0, s[6:7]
	global_load_dwordx4 v[202:205], v[10:11], off
	v_lshl_add_u64 v[10:11], v[10:11], 0, s[6:7]
	global_load_dwordx4 v[206:209], v[10:11], off
	v_mul_lo_u32 v9, v9, s20
	v_lshlrev_b32_e32 v14, 1, v14
	v_add3_u32 v2, 0, v9, v14
	s_waitcnt vmcnt(7)
	v_cvt_pk_f16_f32 v178, v178, v179
	v_cvt_pk_f16_f32 v179, v180, v181
	ds_write_b64 v2, v[178:179]
	s_waitcnt vmcnt(6)
	v_cvt_pk_f16_f32 v182, v182, v183
	v_cvt_pk_f16_f32 v183, v184, v185
	ds_write_b64 v2, v[182:183] offset:4352
	s_waitcnt vmcnt(5)
	v_cvt_pk_f16_f32 v186, v186, v187
	v_cvt_pk_f16_f32 v187, v188, v189
	ds_write_b64 v2, v[186:187] offset:8704
	s_waitcnt vmcnt(4)
	v_cvt_pk_f16_f32 v190, v190, v191
	v_cvt_pk_f16_f32 v191, v192, v193
	ds_write_b64 v2, v[190:191] offset:13056
	s_waitcnt vmcnt(3)
	v_cvt_pk_f16_f32 v194, v194, v195
	v_cvt_pk_f16_f32 v195, v196, v197
	ds_write_b64 v2, v[194:195] offset:17408
	s_waitcnt vmcnt(2)
	v_cvt_pk_f16_f32 v198, v198, v199
	v_cvt_pk_f16_f32 v199, v200, v201
	ds_write_b64 v2, v[198:199] offset:21760
	s_waitcnt vmcnt(1)
	v_cvt_pk_f16_f32 v202, v202, v203
	v_cvt_pk_f16_f32 v203, v204, v205
	ds_write_b64 v2, v[202:203] offset:26112
	s_waitcnt vmcnt(0)
	v_cvt_pk_f16_f32 v206, v206, v207
	v_cvt_pk_f16_f32 v207, v208, v209
	ds_write_b64 v2, v[206:207] offset:30464
	s_mov_b64 s[4:5], exec
.LBB0_301:
	s_or_b64 exec, exec, s[2:3]
	v_lshl_add_u32 v0, v4, 5, v155
	v_ashrrev_i32_e32 v10, 6, v7
	s_movk_i32 s2, 0x80
	v_and_b32_e32 v9, 0x7fffff80, v0
	v_and_b32_e32 v6, 63, v7
	v_cmp_gt_i32_e32 vcc, s2, v10
	v_lshlrev_b32_e32 v8, 7, v5
	s_and_saveexec_b64 s[2:3], vcc
	s_cbranch_execz .LBB0_304
	v_readlane_b32 s4, v254, 5
	v_lshlrev_b32_e32 v2, 2, v8
	v_readlane_b32 s16, v254, 17
	v_readlane_b32 s17, v254, 18
	v_cmp_lt_i32_e32 vcc, v157, v158
	v_lshlrev_b32_e32 v4, 1, v10
	v_lshl_add_u64 v[0:1], s[16:17], 0, v[2:3]
	v_lshlrev_b32_e32 v2, 3, v6
	v_lshl_add_u64 v[0:1], v[0:1], 0, v[2:3]
	global_load_dwordx2 v[0:1], v[0:1], off
	v_cndmask_b32_e32 v2, v156, v157, vcc
	v_cmp_lt_i32_e32 vcc, v159, v158
	v_lshlrev_b32_e32 v11, 2, v2
	v_readlane_b32 s4, v255, 30
	v_cndmask_b32_e32 v2, v156, v159, vcc
	v_lshlrev_b32_e32 v12, 2, v2
	v_mul_u32_u24_e32 v2, 0x220, v6
	v_readlane_b32 s5, v254, 6
	v_add3_u32 v13, v2, v4, s4
	v_add_u32_e32 v4, v10, v9
	v_lshlrev_b32_e32 v2, 8, v5
	v_mad_i64_i32 v[4:5], s[4:5], v4, s87, v[2:3]
	v_lshlrev_b32_e32 v2, 2, v6
	v_readlane_b32 s4, v255, 26
	v_lshl_add_u64 v[4:5], v[4:5], 0, v[2:3]
	v_readlane_b32 s5, v255, 27
	v_add_u32_e32 v14, -8, v10
	v_readlane_b32 s6, v254, 7
	v_lshl_add_u64 v[4:5], s[4:5], 0, v[4:5]
	s_mov_b64 s[4:5], 0
	v_readlane_b32 s7, v254, 8
	v_readlane_b32 s8, v254, 9
	v_readlane_b32 s9, v254, 10
	v_readlane_b32 s10, v254, 11
	v_readlane_b32 s11, v254, 12
	v_readlane_b32 s12, v254, 13
	v_readlane_b32 s13, v254, 14
	v_readlane_b32 s14, v254, 15
	v_readlane_b32 s15, v254, 16
	v_readlane_b32 s18, v254, 19
	v_readlane_b32 s19, v254, 20
	v_cvt_f32_f16_sdwa v194, v210 dst_sel:DWORD dst_unused:UNUSED_PAD src0_sel:WORD_1
	v_cvt_f32_f16_e32 v178, v210
	v_cvt_f32_f16_sdwa v195, v211 dst_sel:DWORD dst_unused:UNUSED_PAD src0_sel:WORD_1
	v_cvt_f32_f16_e32 v179, v211
	v_cvt_f32_f16_sdwa v196, v212 dst_sel:DWORD dst_unused:UNUSED_PAD src0_sel:WORD_1
	v_cvt_f32_f16_e32 v180, v212
	v_cvt_f32_f16_sdwa v197, v213 dst_sel:DWORD dst_unused:UNUSED_PAD src0_sel:WORD_1
	v_cvt_f32_f16_e32 v181, v213
	v_cvt_f32_f16_sdwa v198, v214 dst_sel:DWORD dst_unused:UNUSED_PAD src0_sel:WORD_1
	v_cvt_f32_f16_e32 v182, v214
	v_cvt_f32_f16_sdwa v199, v215 dst_sel:DWORD dst_unused:UNUSED_PAD src0_sel:WORD_1
	v_cvt_f32_f16_e32 v183, v215
	v_cvt_f32_f16_sdwa v200, v216 dst_sel:DWORD dst_unused:UNUSED_PAD src0_sel:WORD_1
	v_cvt_f32_f16_e32 v184, v216
	v_cvt_f32_f16_sdwa v201, v217 dst_sel:DWORD dst_unused:UNUSED_PAD src0_sel:WORD_1
	v_cvt_f32_f16_e32 v185, v217
	v_cvt_f32_f16_sdwa v202, v218 dst_sel:DWORD dst_unused:UNUSED_PAD src0_sel:WORD_1
	v_cvt_f32_f16_e32 v186, v218
	v_cvt_f32_f16_sdwa v203, v219 dst_sel:DWORD dst_unused:UNUSED_PAD src0_sel:WORD_1
	v_cvt_f32_f16_e32 v187, v219
	v_cvt_f32_f16_sdwa v204, v220 dst_sel:DWORD dst_unused:UNUSED_PAD src0_sel:WORD_1
	v_cvt_f32_f16_e32 v188, v220
	v_cvt_f32_f16_sdwa v205, v221 dst_sel:DWORD dst_unused:UNUSED_PAD src0_sel:WORD_1
	v_cvt_f32_f16_e32 v189, v221
	v_cvt_f32_f16_sdwa v206, v222 dst_sel:DWORD dst_unused:UNUSED_PAD src0_sel:WORD_1
	v_cvt_f32_f16_e32 v190, v222
	v_cvt_f32_f16_sdwa v207, v223 dst_sel:DWORD dst_unused:UNUSED_PAD src0_sel:WORD_1
	v_cvt_f32_f16_e32 v191, v223
	v_cvt_f32_f16_sdwa v208, v224 dst_sel:DWORD dst_unused:UNUSED_PAD src0_sel:WORD_1
	v_cvt_f32_f16_e32 v192, v224
	v_cvt_f32_f16_sdwa v209, v225 dst_sel:DWORD dst_unused:UNUSED_PAD src0_sel:WORD_1
	v_cvt_f32_f16_e32 v193, v225
	v_mul_f32_e32 v226, v178, v178
	v_mul_f32_e32 v227, v179, v179
	v_mul_f32_e32 v228, v180, v180
	v_mul_f32_e32 v229, v181, v181
	v_mul_f32_e32 v230, v182, v182
	v_mul_f32_e32 v231, v183, v183
	v_mul_f32_e32 v232, v184, v184
	v_mul_f32_e32 v233, v185, v185
	v_mul_f32_e32 v234, v186, v186
	v_mul_f32_e32 v235, v187, v187
	v_mul_f32_e32 v236, v188, v188
	v_mul_f32_e32 v237, v189, v189
	v_mul_f32_e32 v240, v190, v190
	v_mul_f32_e32 v241, v191, v191
	v_mul_f32_e32 v242, v192, v192
	v_mul_f32_e32 v243, v193, v193
	v_mul_f32_e32 v210, v194, v194
	v_mul_f32_e32 v211, v195, v195
	v_mul_f32_e32 v212, v196, v196
	v_mul_f32_e32 v213, v197, v197
	v_mul_f32_e32 v214, v198, v198
	v_mul_f32_e32 v215, v199, v199
	v_mul_f32_e32 v216, v200, v200
	v_mul_f32_e32 v217, v201, v201
	v_mul_f32_e32 v218, v202, v202
	v_mul_f32_e32 v219, v203, v203
	v_mul_f32_e32 v220, v204, v204
	v_mul_f32_e32 v221, v205, v205
	v_mul_f32_e32 v222, v206, v206
	v_mul_f32_e32 v223, v207, v207
	v_mul_f32_e32 v224, v208, v208
	v_mul_f32_e32 v225, v209, v209
	v_add_f32_e32 v210, v226, v210
	v_add_f32_e32 v211, v227, v211
	v_add_f32_e32 v212, v228, v212
	v_add_f32_e32 v213, v229, v213
	v_add_f32_e32 v214, v230, v214
	v_add_f32_e32 v215, v231, v215
	v_add_f32_e32 v216, v232, v216
	v_add_f32_e32 v217, v233, v217
	v_add_f32_e32 v218, v234, v218
	v_add_f32_e32 v219, v235, v219
	v_add_f32_e32 v220, v236, v220
	v_add_f32_e32 v221, v237, v221
	v_add_f32_e32 v222, v240, v222
	v_add_f32_e32 v223, v241, v223
	v_add_f32_e32 v224, v242, v224
	v_add_f32_e32 v225, v243, v225
	v_add_f32_dpp v210, v210, v210 quad_perm:[1,0,3,2] row_mask:0xf bank_mask:0xf bound_ctrl:1
	v_add_f32_dpp v211, v211, v211 quad_perm:[1,0,3,2] row_mask:0xf bank_mask:0xf bound_ctrl:1
	v_add_f32_dpp v212, v212, v212 quad_perm:[1,0,3,2] row_mask:0xf bank_mask:0xf bound_ctrl:1
	v_add_f32_dpp v213, v213, v213 quad_perm:[1,0,3,2] row_mask:0xf bank_mask:0xf bound_ctrl:1
	v_add_f32_dpp v214, v214, v214 quad_perm:[1,0,3,2] row_mask:0xf bank_mask:0xf bound_ctrl:1
	v_add_f32_dpp v215, v215, v215 quad_perm:[1,0,3,2] row_mask:0xf bank_mask:0xf bound_ctrl:1
	v_add_f32_dpp v216, v216, v216 quad_perm:[1,0,3,2] row_mask:0xf bank_mask:0xf bound_ctrl:1
	v_add_f32_dpp v217, v217, v217 quad_perm:[1,0,3,2] row_mask:0xf bank_mask:0xf bound_ctrl:1
	v_add_f32_dpp v218, v218, v218 quad_perm:[1,0,3,2] row_mask:0xf bank_mask:0xf bound_ctrl:1
	v_add_f32_dpp v219, v219, v219 quad_perm:[1,0,3,2] row_mask:0xf bank_mask:0xf bound_ctrl:1
	v_add_f32_dpp v220, v220, v220 quad_perm:[1,0,3,2] row_mask:0xf bank_mask:0xf bound_ctrl:1
	v_add_f32_dpp v221, v221, v221 quad_perm:[1,0,3,2] row_mask:0xf bank_mask:0xf bound_ctrl:1
	v_add_f32_dpp v222, v222, v222 quad_perm:[1,0,3,2] row_mask:0xf bank_mask:0xf bound_ctrl:1
	v_add_f32_dpp v223, v223, v223 quad_perm:[1,0,3,2] row_mask:0xf bank_mask:0xf bound_ctrl:1
	v_add_f32_dpp v224, v224, v224 quad_perm:[1,0,3,2] row_mask:0xf bank_mask:0xf bound_ctrl:1
	v_add_f32_dpp v225, v225, v225 quad_perm:[1,0,3,2] row_mask:0xf bank_mask:0xf bound_ctrl:1
	v_add_f32_dpp v210, v210, v210 quad_perm:[2,3,0,1] row_mask:0xf bank_mask:0xf bound_ctrl:1
	v_add_f32_dpp v211, v211, v211 quad_perm:[2,3,0,1] row_mask:0xf bank_mask:0xf bound_ctrl:1
	v_add_f32_dpp v212, v212, v212 quad_perm:[2,3,0,1] row_mask:0xf bank_mask:0xf bound_ctrl:1
	v_add_f32_dpp v213, v213, v213 quad_perm:[2,3,0,1] row_mask:0xf bank_mask:0xf bound_ctrl:1
	v_add_f32_dpp v214, v214, v214 quad_perm:[2,3,0,1] row_mask:0xf bank_mask:0xf bound_ctrl:1
	v_add_f32_dpp v215, v215, v215 quad_perm:[2,3,0,1] row_mask:0xf bank_mask:0xf bound_ctrl:1
	v_add_f32_dpp v216, v216, v216 quad_perm:[2,3,0,1] row_mask:0xf bank_mask:0xf bound_ctrl:1
	v_add_f32_dpp v217, v217, v217 quad_perm:[2,3,0,1] row_mask:0xf bank_mask:0xf bound_ctrl:1
	v_add_f32_dpp v218, v218, v218 quad_perm:[2,3,0,1] row_mask:0xf bank_mask:0xf bound_ctrl:1
	v_add_f32_dpp v219, v219, v219 quad_perm:[2,3,0,1] row_mask:0xf bank_mask:0xf bound_ctrl:1
	v_add_f32_dpp v220, v220, v220 quad_perm:[2,3,0,1] row_mask:0xf bank_mask:0xf bound_ctrl:1
	v_add_f32_dpp v221, v221, v221 quad_perm:[2,3,0,1] row_mask:0xf bank_mask:0xf bound_ctrl:1
	v_add_f32_dpp v222, v222, v222 quad_perm:[2,3,0,1] row_mask:0xf bank_mask:0xf bound_ctrl:1
	v_add_f32_dpp v223, v223, v223 quad_perm:[2,3,0,1] row_mask:0xf bank_mask:0xf bound_ctrl:1
	v_add_f32_dpp v224, v224, v224 quad_perm:[2,3,0,1] row_mask:0xf bank_mask:0xf bound_ctrl:1
	v_add_f32_dpp v225, v225, v225 quad_perm:[2,3,0,1] row_mask:0xf bank_mask:0xf bound_ctrl:1
	v_add_f32_dpp v210, v210, v210 row_half_mirror row_mask:0xf bank_mask:0xf bound_ctrl:1
	v_add_f32_dpp v211, v211, v211 row_half_mirror row_mask:0xf bank_mask:0xf bound_ctrl:1
	v_add_f32_dpp v212, v212, v212 row_half_mirror row_mask:0xf bank_mask:0xf bound_ctrl:1
	v_add_f32_dpp v213, v213, v213 row_half_mirror row_mask:0xf bank_mask:0xf bound_ctrl:1
	v_add_f32_dpp v214, v214, v214 row_half_mirror row_mask:0xf bank_mask:0xf bound_ctrl:1
	v_add_f32_dpp v215, v215, v215 row_half_mirror row_mask:0xf bank_mask:0xf bound_ctrl:1
	v_add_f32_dpp v216, v216, v216 row_half_mirror row_mask:0xf bank_mask:0xf bound_ctrl:1
	v_add_f32_dpp v217, v217, v217 row_half_mirror row_mask:0xf bank_mask:0xf bound_ctrl:1
	v_add_f32_dpp v218, v218, v218 row_half_mirror row_mask:0xf bank_mask:0xf bound_ctrl:1
	v_add_f32_dpp v219, v219, v219 row_half_mirror row_mask:0xf bank_mask:0xf bound_ctrl:1
	v_add_f32_dpp v220, v220, v220 row_half_mirror row_mask:0xf bank_mask:0xf bound_ctrl:1
	v_add_f32_dpp v221, v221, v221 row_half_mirror row_mask:0xf bank_mask:0xf bound_ctrl:1
	v_add_f32_dpp v222, v222, v222 row_half_mirror row_mask:0xf bank_mask:0xf bound_ctrl:1
	v_add_f32_dpp v223, v223, v223 row_half_mirror row_mask:0xf bank_mask:0xf bound_ctrl:1
	v_add_f32_dpp v224, v224, v224 row_half_mirror row_mask:0xf bank_mask:0xf bound_ctrl:1
	v_add_f32_dpp v225, v225, v225 row_half_mirror row_mask:0xf bank_mask:0xf bound_ctrl:1
	v_add_f32_dpp v210, v210, v210 row_mirror row_mask:0xf bank_mask:0xf bound_ctrl:1
	v_add_f32_dpp v211, v211, v211 row_mirror row_mask:0xf bank_mask:0xf bound_ctrl:1
	v_add_f32_dpp v212, v212, v212 row_mirror row_mask:0xf bank_mask:0xf bound_ctrl:1
	v_add_f32_dpp v213, v213, v213 row_mirror row_mask:0xf bank_mask:0xf bound_ctrl:1
	v_add_f32_dpp v214, v214, v214 row_mirror row_mask:0xf bank_mask:0xf bound_ctrl:1
	v_add_f32_dpp v215, v215, v215 row_mirror row_mask:0xf bank_mask:0xf bound_ctrl:1
	v_add_f32_dpp v216, v216, v216 row_mirror row_mask:0xf bank_mask:0xf bound_ctrl:1
	v_add_f32_dpp v217, v217, v217 row_mirror row_mask:0xf bank_mask:0xf bound_ctrl:1
	v_add_f32_dpp v218, v218, v218 row_mirror row_mask:0xf bank_mask:0xf bound_ctrl:1
	v_add_f32_dpp v219, v219, v219 row_mirror row_mask:0xf bank_mask:0xf bound_ctrl:1
	v_add_f32_dpp v220, v220, v220 row_mirror row_mask:0xf bank_mask:0xf bound_ctrl:1
	v_add_f32_dpp v221, v221, v221 row_mirror row_mask:0xf bank_mask:0xf bound_ctrl:1
	v_add_f32_dpp v222, v222, v222 row_mirror row_mask:0xf bank_mask:0xf bound_ctrl:1
	v_add_f32_dpp v223, v223, v223 row_mirror row_mask:0xf bank_mask:0xf bound_ctrl:1
	v_add_f32_dpp v224, v224, v224 row_mirror row_mask:0xf bank_mask:0xf bound_ctrl:1
	v_add_f32_dpp v225, v225, v225 row_mirror row_mask:0xf bank_mask:0xf bound_ctrl:1
	ds_bpermute_b32 v226, v11, v210
	ds_bpermute_b32 v227, v11, v211
	ds_bpermute_b32 v228, v11, v212
	ds_bpermute_b32 v229, v11, v213
	ds_bpermute_b32 v230, v11, v214
	ds_bpermute_b32 v231, v11, v215
	ds_bpermute_b32 v232, v11, v216
	ds_bpermute_b32 v233, v11, v217
	ds_bpermute_b32 v234, v11, v218
	ds_bpermute_b32 v235, v11, v219
	ds_bpermute_b32 v236, v11, v220
	ds_bpermute_b32 v237, v11, v221
	ds_bpermute_b32 v240, v11, v222
	ds_bpermute_b32 v241, v11, v223
	ds_bpermute_b32 v242, v11, v224
	ds_bpermute_b32 v243, v11, v225
	s_waitcnt lgkmcnt(0)
	v_add_f32_e32 v210, v210, v226
	v_add_f32_e32 v211, v211, v227
	v_add_f32_e32 v212, v212, v228
	v_add_f32_e32 v213, v213, v229
	v_add_f32_e32 v214, v214, v230
	v_add_f32_e32 v215, v215, v231
	v_add_f32_e32 v216, v216, v232
	v_add_f32_e32 v217, v217, v233
	v_add_f32_e32 v218, v218, v234
	v_add_f32_e32 v219, v219, v235
	v_add_f32_e32 v220, v220, v236
	v_add_f32_e32 v221, v221, v237
	v_add_f32_e32 v222, v222, v240
	v_add_f32_e32 v223, v223, v241
	v_add_f32_e32 v224, v224, v242
	v_add_f32_e32 v225, v225, v243
	ds_bpermute_b32 v226, v12, v210
	ds_bpermute_b32 v227, v12, v211
	ds_bpermute_b32 v228, v12, v212
	ds_bpermute_b32 v229, v12, v213
	ds_bpermute_b32 v230, v12, v214
	ds_bpermute_b32 v231, v12, v215
	ds_bpermute_b32 v232, v12, v216
	ds_bpermute_b32 v233, v12, v217
	ds_bpermute_b32 v234, v12, v218
	ds_bpermute_b32 v235, v12, v219
	ds_bpermute_b32 v236, v12, v220
	ds_bpermute_b32 v237, v12, v221
	ds_bpermute_b32 v240, v12, v222
	ds_bpermute_b32 v241, v12, v223
	ds_bpermute_b32 v242, v12, v224
	ds_bpermute_b32 v243, v12, v225
	s_waitcnt lgkmcnt(0)
	v_add_f32_e32 v210, v210, v226
	v_add_f32_e32 v211, v211, v227
	v_add_f32_e32 v212, v212, v228
	v_add_f32_e32 v213, v213, v229
	v_add_f32_e32 v214, v214, v230
	v_add_f32_e32 v215, v215, v231
	v_add_f32_e32 v216, v216, v232
	v_add_f32_e32 v217, v217, v233
	v_add_f32_e32 v218, v218, v234
	v_add_f32_e32 v219, v219, v235
	v_add_f32_e32 v220, v220, v236
	v_add_f32_e32 v221, v221, v237
	v_add_f32_e32 v222, v222, v240
	v_add_f32_e32 v223, v223, v241
	v_add_f32_e32 v224, v224, v242
	v_add_f32_e32 v225, v225, v243
	v_fmamk_f32 v210, v210, 0x3c000000, v154
	v_fmamk_f32 v211, v211, 0x3c000000, v154
	v_fmamk_f32 v212, v212, 0x3c000000, v154
	v_fmamk_f32 v213, v213, 0x3c000000, v154
	v_fmamk_f32 v214, v214, 0x3c000000, v154
	v_fmamk_f32 v215, v215, 0x3c000000, v154
	v_fmamk_f32 v216, v216, 0x3c000000, v154
	v_fmamk_f32 v217, v217, 0x3c000000, v154
	v_fmamk_f32 v218, v218, 0x3c000000, v154
	v_fmamk_f32 v219, v219, 0x3c000000, v154
	v_fmamk_f32 v220, v220, 0x3c000000, v154
	v_fmamk_f32 v221, v221, 0x3c000000, v154
	v_fmamk_f32 v222, v222, 0x3c000000, v154
	v_fmamk_f32 v223, v223, 0x3c000000, v154
	v_fmamk_f32 v224, v224, 0x3c000000, v154
	v_fmamk_f32 v225, v225, 0x3c000000, v154
	v_rsq_f32_e32 v210, v210
	v_rsq_f32_e32 v211, v211
	v_rsq_f32_e32 v212, v212
	v_rsq_f32_e32 v213, v213
	v_rsq_f32_e32 v214, v214
	v_rsq_f32_e32 v215, v215
	v_rsq_f32_e32 v216, v216
	v_rsq_f32_e32 v217, v217
	v_rsq_f32_e32 v218, v218
	v_rsq_f32_e32 v219, v219
	v_rsq_f32_e32 v220, v220
	v_rsq_f32_e32 v221, v221
	v_rsq_f32_e32 v222, v222
	v_rsq_f32_e32 v223, v223
	v_rsq_f32_e32 v224, v224
	v_rsq_f32_e32 v225, v225
	v_mul_f32_e32 v226, v210, v178
	v_mul_f32_e32 v227, v211, v179
	v_mul_f32_e32 v228, v212, v180
	v_mul_f32_e32 v229, v213, v181
	v_mul_f32_e32 v230, v214, v182
	v_mul_f32_e32 v231, v215, v183
	v_mul_f32_e32 v232, v216, v184
	v_mul_f32_e32 v233, v217, v185
	v_mul_f32_e32 v234, v218, v186
	v_mul_f32_e32 v235, v219, v187
	v_mul_f32_e32 v236, v220, v188
	v_mul_f32_e32 v237, v221, v189
	v_mul_f32_e32 v240, v222, v190
	v_mul_f32_e32 v241, v223, v191
	v_mul_f32_e32 v242, v224, v192
	v_mul_f32_e32 v243, v225, v193
	v_mul_f32_e32 v210, v210, v194
	v_mul_f32_e32 v211, v211, v195
	v_mul_f32_e32 v212, v212, v196
	v_mul_f32_e32 v213, v213, v197
	v_mul_f32_e32 v214, v214, v198
	v_mul_f32_e32 v215, v215, v199
	v_mul_f32_e32 v216, v216, v200
	v_mul_f32_e32 v217, v217, v201
	v_mul_f32_e32 v218, v218, v202
	v_mul_f32_e32 v219, v219, v203
	v_mul_f32_e32 v220, v220, v204
	v_mul_f32_e32 v221, v221, v205
	v_mul_f32_e32 v222, v222, v206
	v_mul_f32_e32 v223, v223, v207
	v_mul_f32_e32 v224, v224, v208
	v_mul_f32_e32 v225, v225, v209
	s_waitcnt vmcnt(0)
	v_fma_mixlo_f16 v226, v0, v226, 0
	v_fma_mixlo_f16 v227, v0, v227, 0
	v_fma_mixlo_f16 v228, v0, v228, 0
	v_fma_mixlo_f16 v229, v0, v229, 0
	v_fma_mixlo_f16 v230, v0, v230, 0
	v_fma_mixlo_f16 v231, v0, v231, 0
	v_fma_mixlo_f16 v232, v0, v232, 0
	v_fma_mixlo_f16 v233, v0, v233, 0
	v_fma_mixlo_f16 v234, v0, v234, 0
	v_fma_mixlo_f16 v235, v0, v235, 0
	v_fma_mixlo_f16 v236, v0, v236, 0
	v_fma_mixlo_f16 v237, v0, v237, 0
	v_fma_mixlo_f16 v240, v0, v240, 0
	v_fma_mixlo_f16 v241, v0, v241, 0
	v_fma_mixlo_f16 v242, v0, v242, 0
	v_fma_mixlo_f16 v243, v0, v243, 0
	v_fma_mixlo_f16 v210, v1, v210, 0
	v_fma_mixlo_f16 v211, v1, v211, 0
	v_fma_mixlo_f16 v212, v1, v212, 0
	v_fma_mixlo_f16 v213, v1, v213, 0
	v_fma_mixlo_f16 v214, v1, v214, 0
	v_fma_mixlo_f16 v215, v1, v215, 0
	v_fma_mixlo_f16 v216, v1, v216, 0
	v_fma_mixlo_f16 v217, v1, v217, 0
	v_fma_mixlo_f16 v218, v1, v218, 0
	v_fma_mixlo_f16 v219, v1, v219, 0
	v_fma_mixlo_f16 v220, v1, v220, 0
	v_fma_mixlo_f16 v221, v1, v221, 0
	v_fma_mixlo_f16 v222, v1, v222, 0
	v_fma_mixlo_f16 v223, v1, v223, 0
	v_fma_mixlo_f16 v224, v1, v224, 0
	v_fma_mixlo_f16 v225, v1, v225, 0
	ds_write_b16 v13, v226
	ds_write_b16 v13, v210 offset:272
	ds_write_b16 v13, v227 offset:16
	ds_write_b16 v13, v211 offset:288
	ds_write_b16 v13, v228 offset:32
	ds_write_b16 v13, v212 offset:304
	ds_write_b16 v13, v229 offset:48
	ds_write_b16 v13, v213 offset:320
	ds_write_b16 v13, v230 offset:64
	ds_write_b16 v13, v214 offset:336
	ds_write_b16 v13, v231 offset:80
	ds_write_b16 v13, v215 offset:352
	ds_write_b16 v13, v232 offset:96
	ds_write_b16 v13, v216 offset:368
	ds_write_b16 v13, v233 offset:112
	ds_write_b16 v13, v217 offset:384
	ds_write_b16 v13, v234 offset:128
	ds_write_b16 v13, v218 offset:400
	ds_write_b16 v13, v235 offset:144
	ds_write_b16 v13, v219 offset:416
	ds_write_b16 v13, v236 offset:160
	ds_write_b16 v13, v220 offset:432
	ds_write_b16 v13, v237 offset:176
	ds_write_b16 v13, v221 offset:448
	ds_write_b16 v13, v240 offset:192
	ds_write_b16 v13, v222 offset:464
	ds_write_b16 v13, v241 offset:208
	ds_write_b16 v13, v223 offset:480
	ds_write_b16 v13, v242 offset:224
	ds_write_b16 v13, v224 offset:496
	ds_write_b16 v13, v243 offset:240
	ds_write_b16 v13, v225 offset:512
	s_mov_b64 s[4:5], exec
.LBB0_304:
	s_or_b64 exec, exec, s[2:3]
	v_and_b32_e32 v7, 15, v7
	v_lshl_or_b32 v10, v10, 4, v7
	v_lshrrev_b32_e32 v0, 1, v6
	v_and_b32_e32 v20, 24, v0
	v_add_u32_e32 v0, v10, v8
	v_readlane_b32 s4, v254, 53
	v_ashrrev_i32_e32 v1, 31, v0
	v_readlane_b32 s5, v254, 54
	v_readlane_b32 s6, v254, 55
	v_readlane_b32 s7, v254, 56
	v_readlane_b32 s8, v254, 57
	v_readlane_b32 s9, v254, 58
	v_readlane_b32 s10, v254, 59
	v_readlane_b32 s11, v254, 60
	v_readlane_b32 s12, v254, 61
	v_readlane_b32 s13, v254, 62
	v_readlane_b32 s14, v254, 63
	v_readlane_b32 s15, v255, 0
	v_readlane_b32 s16, v255, 1
	v_readlane_b32 s17, v255, 2
	v_readlane_b32 s18, v255, 3
	v_readlane_b32 s19, v255, 4
	v_lshl_add_u64 v[0:1], v[0:1], 2, s[4:5]
	v_readlane_b32 s4, v254, 21
	v_readlane_b32 s6, v254, 23
	v_readlane_b32 s7, v254, 24
	v_add_u32_e32 v22, v10, v9
	v_lshlrev_b32_e32 v2, 1, v8
	v_mov_b64_e32 v[4:5], s[6:7]
	v_mad_i64_i32 v[4:5], s[2:3], v22, s87, v[4:5]
	v_lshl_add_u64 v[4:5], v[4:5], 0, v[2:3]
	v_mov_b32_e32 v21, v3
	v_lshl_add_u64 v[24:25], v[4:5], 0, v[20:21]
	s_movk_i32 s2, 0x1000
	v_add_co_u32_e32 v4, vcc, s2, v24
	s_waitcnt lgkmcnt(0)
	s_nop 0
	v_addc_co_u32_e32 v5, vcc, 0, v25, vcc
	s_barrier
	global_load_dword v0, v[0:1], off
	s_nop 0
	v_and_b32_e32 v1, 48, v6
	v_add_u32_e32 v8, 0, v1
	s_movk_i32 s2, 0x110
	v_mad_u32_u24 v1, v7, s2, v8
	ds_read_b128 v[4:7], v1 offset:34816
	v_mad_u64_u32 v[40:41], s[2:3], v10, s2, v[8:9]
	ds_read_b128 v[16:19], v40
	ds_read_b128 v[28:31], v1 offset:34880
	ds_read_b128 v[12:15], v40 offset:64
	ds_read_b128 v[32:35], v1 offset:34944
	s_waitcnt lgkmcnt(3)
	v_mfma_f32_16x16x32_f16 v[36:39], v[4:7], v[16:19], 0
	ds_read_b128 v[8:11], v40 offset:128
	ds_read_b128 v[4:7], v40 offset:192
	ds_read_b128 v[40:43], v1 offset:35008
	v_ashrrev_i32_e32 v23, 31, v22
	v_readlane_b32 s5, v254, 22
	s_waitcnt lgkmcnt(4)
	v_mfma_f32_16x16x32_f16 v[28:31], v[28:31], v[12:15], v[36:39]
	v_lshlrev_b64 v[22:23], 12, v[22:23]
	v_lshl_add_u64 v[22:23], s[4:5], 0, v[22:23]
	s_mov_b64 s[2:3], 0x1a20
	s_waitcnt lgkmcnt(2)
	v_mfma_f32_16x16x32_f16 v[28:31], v[32:35], v[8:11], v[28:31]
	v_lshl_add_u64 v[32:33], v[22:23], 0, v[2:3]
	v_lshl_add_u64 v[20:21], v[32:33], 0, v[20:21]
	v_lshl_add_u64 v[22:23], v[24:25], 0, s[2:3]
	s_waitcnt lgkmcnt(0)
	v_mfma_f32_16x16x32_f16 v[28:31], v[40:43], v[4:7], v[28:31]
	s_mov_b64 s[2:3], 0x1220
	v_lshl_add_u64 v[24:25], v[24:25], 0, s[2:3]
	v_readlane_b32 s8, v254, 25
	v_readlane_b32 s9, v254, 26
	v_readlane_b32 s10, v254, 27
	v_readlane_b32 s11, v254, 28
	v_readlane_b32 s12, v254, 29
	v_readlane_b32 s13, v254, 30
	v_readlane_b32 s14, v254, 31
	v_readlane_b32 s15, v254, 32
	v_readlane_b32 s16, v254, 33
	v_readlane_b32 s17, v254, 34
	v_readlane_b32 s18, v254, 35
	v_readlane_b32 s19, v254, 36
	s_waitcnt vmcnt(0)
	v_pk_add_f32 v[28:29], v[28:29], v[0:1] op_sel_hi:[1,0]
	v_cvt_f32_f16_e32 v32, v126
	v_cvt_f32_f16_sdwa v33, v126 dst_sel:DWORD dst_unused:UNUSED_PAD src0_sel:WORD_1
	v_cvt_f32_f16_e32 v36, v127
	v_cvt_f32_f16_sdwa v37, v127 dst_sel:DWORD dst_unused:UNUSED_PAD src0_sel:WORD_1
	v_mul_f32_e32 v2, 0xbfb8aa3b, v32
	v_mul_f32_e32 v38, 0xbfb8aa3b, v33
	v_mul_f32_e32 v39, 0xbfb8aa3b, v36
	v_mul_f32_e32 v40, 0xbfb8aa3b, v37
	v_exp_f32_e32 v2, v2
	v_exp_f32_e32 v38, v38
	v_exp_f32_e32 v39, v39
	v_exp_f32_e32 v40, v40
	v_add_f32_e32 v2, 1.0, v2
	v_add_f32_e32 v41, 1.0, v38
	v_add_f32_e32 v42, 1.0, v39
	v_add_f32_e32 v43, 1.0, v40
	v_cvt_f32_f16_e32 v34, v142
	v_cvt_f32_f16_sdwa v35, v142 dst_sel:DWORD dst_unused:UNUSED_PAD src0_sel:WORD_1
	v_cvt_f32_f16_e32 v26, v143
	v_cvt_f32_f16_sdwa v27, v143 dst_sel:DWORD dst_unused:UNUSED_PAD src0_sel:WORD_1
	v_rcp_f32_e32 v38, v2
	v_rcp_f32_e32 v39, v41
	v_rcp_f32_e32 v40, v42
	v_rcp_f32_e32 v41, v43
	v_pk_add_f32 v[30:31], v[30:31], v[0:1] op_sel_hi:[1,0]
	v_pk_mul_f32 v[28:29], v[28:29], v[34:35]
	v_pk_mul_f32 v[26:27], v[30:31], v[26:27]
	v_pk_mul_f32 v[30:31], v[38:39], v[32:33]
	v_pk_mul_f32 v[32:33], v[40:41], v[36:37]
	v_pk_mul_f32 v[28:29], v[28:29], v[30:31]
	v_pk_mul_f32 v[26:27], v[26:27], v[32:33]
	v_cvt_pk_f16_f32 v28, v28, v29
	v_cvt_pk_f16_f32 v29, v26, v27
	global_store_dwordx2 v[20:21], v[28:29], off offset:1536
	ds_read_b128 v[26:29], v1 offset:39168
	ds_read_b128 v[30:33], v1 offset:39232
	s_waitcnt lgkmcnt(1)
	v_mfma_f32_16x16x32_f16 v[26:29], v[26:29], v[16:19], 0
	s_waitcnt lgkmcnt(0)
	v_mfma_f32_16x16x32_f16 v[26:29], v[30:33], v[12:15], v[26:29]
	ds_read_b128 v[30:33], v1 offset:39296
	s_waitcnt lgkmcnt(0)
	v_mfma_f32_16x16x32_f16 v[26:29], v[30:33], v[8:11], v[26:29]
	ds_read_b128 v[30:33], v1 offset:39360
	s_waitcnt lgkmcnt(0)
	v_mfma_f32_16x16x32_f16 v[26:29], v[30:33], v[4:7], v[26:29]
	v_cvt_f32_f16_e32 v30, v128
	v_cvt_f32_f16_sdwa v31, v128 dst_sel:DWORD dst_unused:UNUSED_PAD src0_sel:WORD_1
	v_cvt_f32_f16_e32 v34, v129
	v_cvt_f32_f16_sdwa v35, v129 dst_sel:DWORD dst_unused:UNUSED_PAD src0_sel:WORD_1
	v_mul_f32_e32 v2, 0xbfb8aa3b, v30
	v_mul_f32_e32 v38, 0xbfb8aa3b, v31
	v_mul_f32_e32 v39, 0xbfb8aa3b, v34
	v_mul_f32_e32 v40, 0xbfb8aa3b, v35
	v_exp_f32_e32 v2, v2
	v_exp_f32_e32 v38, v38
	v_exp_f32_e32 v39, v39
	v_exp_f32_e32 v40, v40
	v_add_f32_e32 v2, 1.0, v2
	v_add_f32_e32 v41, 1.0, v38
	v_add_f32_e32 v42, 1.0, v39
	v_add_f32_e32 v43, 1.0, v40
	v_cvt_f32_f16_e32 v32, v144
	v_cvt_f32_f16_sdwa v33, v144 dst_sel:DWORD dst_unused:UNUSED_PAD src0_sel:WORD_1
	v_cvt_f32_f16_e32 v36, v145
	v_cvt_f32_f16_sdwa v37, v145 dst_sel:DWORD dst_unused:UNUSED_PAD src0_sel:WORD_1
	v_rcp_f32_e32 v38, v2
	v_rcp_f32_e32 v39, v41
	v_rcp_f32_e32 v40, v42
	v_rcp_f32_e32 v41, v43
	v_pk_add_f32 v[26:27], v[26:27], v[0:1] op_sel_hi:[1,0]
	v_pk_add_f32 v[28:29], v[28:29], v[0:1] op_sel_hi:[1,0]
	v_pk_mul_f32 v[26:27], v[26:27], v[32:33]
	v_pk_mul_f32 v[28:29], v[28:29], v[36:37]
	v_pk_mul_f32 v[30:31], v[38:39], v[30:31]
	v_pk_mul_f32 v[32:33], v[40:41], v[34:35]
	v_pk_mul_f32 v[26:27], v[26:27], v[30:31]
	v_pk_mul_f32 v[28:29], v[28:29], v[32:33]
	v_cvt_pk_f16_f32 v26, v26, v27
	v_cvt_pk_f16_f32 v27, v28, v29
	global_store_dwordx2 v[20:21], v[26:27], off offset:1568
	ds_read_b128 v[26:29], v1 offset:43520
	ds_read_b128 v[30:33], v1 offset:43584
	s_waitcnt lgkmcnt(1)
	v_mfma_f32_16x16x32_f16 v[26:29], v[26:29], v[16:19], 0
	s_waitcnt lgkmcnt(0)
	v_mfma_f32_16x16x32_f16 v[26:29], v[30:33], v[12:15], v[26:29]
	ds_read_b128 v[30:33], v1 offset:43648
	s_waitcnt lgkmcnt(0)
	v_mfma_f32_16x16x32_f16 v[26:29], v[30:33], v[8:11], v[26:29]
	ds_read_b128 v[30:33], v1 offset:43712
	s_waitcnt lgkmcnt(0)
	v_mfma_f32_16x16x32_f16 v[26:29], v[30:33], v[4:7], v[26:29]
	v_cvt_f32_f16_e32 v30, v130
	v_cvt_f32_f16_sdwa v31, v130 dst_sel:DWORD dst_unused:UNUSED_PAD src0_sel:WORD_1
	v_cvt_f32_f16_e32 v34, v131
	v_cvt_f32_f16_sdwa v35, v131 dst_sel:DWORD dst_unused:UNUSED_PAD src0_sel:WORD_1
	v_mul_f32_e32 v2, 0xbfb8aa3b, v30
	v_mul_f32_e32 v38, 0xbfb8aa3b, v31
	v_mul_f32_e32 v39, 0xbfb8aa3b, v34
	v_mul_f32_e32 v40, 0xbfb8aa3b, v35
	v_exp_f32_e32 v2, v2
	v_exp_f32_e32 v38, v38
	v_exp_f32_e32 v39, v39
	v_exp_f32_e32 v40, v40
	v_add_f32_e32 v2, 1.0, v2
	v_add_f32_e32 v41, 1.0, v38
	v_add_f32_e32 v42, 1.0, v39
	v_add_f32_e32 v43, 1.0, v40
	v_cvt_f32_f16_e32 v32, v146
	v_cvt_f32_f16_sdwa v33, v146 dst_sel:DWORD dst_unused:UNUSED_PAD src0_sel:WORD_1
	v_cvt_f32_f16_e32 v36, v147
	v_cvt_f32_f16_sdwa v37, v147 dst_sel:DWORD dst_unused:UNUSED_PAD src0_sel:WORD_1
	v_rcp_f32_e32 v38, v2
	v_rcp_f32_e32 v39, v41
	v_rcp_f32_e32 v40, v42
	v_rcp_f32_e32 v41, v43
	v_pk_add_f32 v[26:27], v[26:27], v[0:1] op_sel_hi:[1,0]
	v_pk_add_f32 v[28:29], v[28:29], v[0:1] op_sel_hi:[1,0]
	v_pk_mul_f32 v[26:27], v[26:27], v[32:33]
	v_pk_mul_f32 v[28:29], v[28:29], v[36:37]
	v_pk_mul_f32 v[30:31], v[38:39], v[30:31]
	v_pk_mul_f32 v[32:33], v[40:41], v[34:35]
	v_pk_mul_f32 v[26:27], v[26:27], v[30:31]
	v_pk_mul_f32 v[28:29], v[28:29], v[32:33]
	v_cvt_pk_f16_f32 v26, v26, v27
	v_cvt_pk_f16_f32 v27, v28, v29
	global_store_dwordx2 v[20:21], v[26:27], off offset:1600
	ds_read_b128 v[26:29], v1 offset:47872
	ds_read_b128 v[30:33], v1 offset:47936
	s_waitcnt lgkmcnt(1)
	v_mfma_f32_16x16x32_f16 v[26:29], v[26:29], v[16:19], 0
	s_waitcnt lgkmcnt(0)
	v_mfma_f32_16x16x32_f16 v[26:29], v[30:33], v[12:15], v[26:29]
	ds_read_b128 v[30:33], v1 offset:48000
	s_waitcnt lgkmcnt(0)
	v_mfma_f32_16x16x32_f16 v[26:29], v[30:33], v[8:11], v[26:29]
	ds_read_b128 v[30:33], v1 offset:48064
	s_waitcnt lgkmcnt(0)
	v_mfma_f32_16x16x32_f16 v[26:29], v[30:33], v[4:7], v[26:29]
	v_cvt_f32_f16_e32 v30, v132
	v_cvt_f32_f16_sdwa v31, v132 dst_sel:DWORD dst_unused:UNUSED_PAD src0_sel:WORD_1
	v_cvt_f32_f16_e32 v34, v133
	v_cvt_f32_f16_sdwa v35, v133 dst_sel:DWORD dst_unused:UNUSED_PAD src0_sel:WORD_1
	v_mul_f32_e32 v2, 0xbfb8aa3b, v30
	v_mul_f32_e32 v38, 0xbfb8aa3b, v31
	v_mul_f32_e32 v39, 0xbfb8aa3b, v34
	v_mul_f32_e32 v40, 0xbfb8aa3b, v35
	v_exp_f32_e32 v2, v2
	v_exp_f32_e32 v38, v38
	v_exp_f32_e32 v39, v39
	v_exp_f32_e32 v40, v40
	v_add_f32_e32 v2, 1.0, v2
	v_add_f32_e32 v41, 1.0, v38
	v_add_f32_e32 v42, 1.0, v39
	v_add_f32_e32 v43, 1.0, v40
	v_cvt_f32_f16_e32 v32, v148
	v_cvt_f32_f16_sdwa v33, v148 dst_sel:DWORD dst_unused:UNUSED_PAD src0_sel:WORD_1
	v_cvt_f32_f16_e32 v36, v149
	v_cvt_f32_f16_sdwa v37, v149 dst_sel:DWORD dst_unused:UNUSED_PAD src0_sel:WORD_1
	v_rcp_f32_e32 v38, v2
	v_rcp_f32_e32 v39, v41
	v_rcp_f32_e32 v40, v42
	v_rcp_f32_e32 v41, v43
	v_pk_add_f32 v[26:27], v[26:27], v[0:1] op_sel_hi:[1,0]
	v_pk_add_f32 v[28:29], v[28:29], v[0:1] op_sel_hi:[1,0]
	v_pk_mul_f32 v[26:27], v[26:27], v[32:33]
	v_pk_mul_f32 v[28:29], v[28:29], v[36:37]
	v_pk_mul_f32 v[30:31], v[38:39], v[30:31]
	v_pk_mul_f32 v[32:33], v[40:41], v[34:35]
	v_pk_mul_f32 v[26:27], v[26:27], v[30:31]
	v_pk_mul_f32 v[28:29], v[28:29], v[32:33]
	v_cvt_pk_f16_f32 v26, v26, v27
	v_cvt_pk_f16_f32 v27, v28, v29
	global_store_dwordx2 v[20:21], v[26:27], off offset:1632
	ds_read_b128 v[26:29], v1 offset:52224
	ds_read_b128 v[30:33], v1 offset:52288
	s_waitcnt lgkmcnt(1)
	v_mfma_f32_16x16x32_f16 v[26:29], v[26:29], v[16:19], 0
	s_waitcnt lgkmcnt(0)
	v_mfma_f32_16x16x32_f16 v[26:29], v[30:33], v[12:15], v[26:29]
	ds_read_b128 v[30:33], v1 offset:52352
	s_waitcnt lgkmcnt(0)
	v_mfma_f32_16x16x32_f16 v[26:29], v[30:33], v[8:11], v[26:29]
	ds_read_b128 v[30:33], v1 offset:52416
	s_waitcnt lgkmcnt(0)
	v_mfma_f32_16x16x32_f16 v[26:29], v[30:33], v[4:7], v[26:29]
	v_cvt_f32_f16_e32 v30, v134
	v_cvt_f32_f16_sdwa v31, v134 dst_sel:DWORD dst_unused:UNUSED_PAD src0_sel:WORD_1
	v_cvt_f32_f16_e32 v34, v135
	v_cvt_f32_f16_sdwa v35, v135 dst_sel:DWORD dst_unused:UNUSED_PAD src0_sel:WORD_1
	v_mul_f32_e32 v2, 0xbfb8aa3b, v30
	v_mul_f32_e32 v38, 0xbfb8aa3b, v31
	v_mul_f32_e32 v39, 0xbfb8aa3b, v34
	v_mul_f32_e32 v40, 0xbfb8aa3b, v35
	v_exp_f32_e32 v2, v2
	v_exp_f32_e32 v38, v38
	v_exp_f32_e32 v39, v39
	v_exp_f32_e32 v40, v40
	v_add_f32_e32 v2, 1.0, v2
	v_add_f32_e32 v41, 1.0, v38
	v_add_f32_e32 v42, 1.0, v39
	v_add_f32_e32 v43, 1.0, v40
	v_cvt_f32_f16_e32 v32, v244
	v_cvt_f32_f16_sdwa v33, v244 dst_sel:DWORD dst_unused:UNUSED_PAD src0_sel:WORD_1
	v_cvt_f32_f16_e32 v36, v245
	v_cvt_f32_f16_sdwa v37, v245 dst_sel:DWORD dst_unused:UNUSED_PAD src0_sel:WORD_1
	v_rcp_f32_e32 v38, v2
	v_rcp_f32_e32 v39, v41
	v_rcp_f32_e32 v40, v42
	v_rcp_f32_e32 v41, v43
	v_pk_add_f32 v[26:27], v[26:27], v[0:1] op_sel_hi:[1,0]
	v_pk_add_f32 v[28:29], v[28:29], v[0:1] op_sel_hi:[1,0]
	v_pk_mul_f32 v[26:27], v[26:27], v[32:33]
	v_pk_mul_f32 v[28:29], v[28:29], v[36:37]
	v_pk_mul_f32 v[30:31], v[38:39], v[30:31]
	v_pk_mul_f32 v[32:33], v[40:41], v[34:35]
	v_pk_mul_f32 v[26:27], v[26:27], v[30:31]
	v_pk_mul_f32 v[28:29], v[28:29], v[32:33]
	v_cvt_pk_f16_f32 v26, v26, v27
	v_cvt_pk_f16_f32 v27, v28, v29
	global_store_dwordx2 v[20:21], v[26:27], off offset:1664
	ds_read_b128 v[26:29], v1 offset:56576
	ds_read_b128 v[30:33], v1 offset:56640
	s_waitcnt lgkmcnt(1)
	v_mfma_f32_16x16x32_f16 v[26:29], v[26:29], v[16:19], 0
	s_waitcnt lgkmcnt(0)
	v_mfma_f32_16x16x32_f16 v[26:29], v[30:33], v[12:15], v[26:29]
	ds_read_b128 v[30:33], v1 offset:56704
	s_waitcnt lgkmcnt(0)
	v_mfma_f32_16x16x32_f16 v[26:29], v[30:33], v[8:11], v[26:29]
	ds_read_b128 v[30:33], v1 offset:56768
	s_waitcnt lgkmcnt(0)
	v_mfma_f32_16x16x32_f16 v[26:29], v[30:33], v[4:7], v[26:29]
	v_cvt_f32_f16_e32 v30, v136
	v_cvt_f32_f16_sdwa v31, v136 dst_sel:DWORD dst_unused:UNUSED_PAD src0_sel:WORD_1
	v_cvt_f32_f16_e32 v34, v137
	v_cvt_f32_f16_sdwa v35, v137 dst_sel:DWORD dst_unused:UNUSED_PAD src0_sel:WORD_1
	v_mul_f32_e32 v2, 0xbfb8aa3b, v30
	v_mul_f32_e32 v38, 0xbfb8aa3b, v31
	v_mul_f32_e32 v39, 0xbfb8aa3b, v34
	v_mul_f32_e32 v40, 0xbfb8aa3b, v35
	v_exp_f32_e32 v2, v2
	v_exp_f32_e32 v38, v38
	v_exp_f32_e32 v39, v39
	v_exp_f32_e32 v40, v40
	v_add_f32_e32 v2, 1.0, v2
	v_add_f32_e32 v41, 1.0, v38
	v_add_f32_e32 v42, 1.0, v39
	v_add_f32_e32 v43, 1.0, v40
	v_cvt_f32_f16_e32 v32, v246
	v_cvt_f32_f16_sdwa v33, v246 dst_sel:DWORD dst_unused:UNUSED_PAD src0_sel:WORD_1
	v_cvt_f32_f16_e32 v36, v247
	v_cvt_f32_f16_sdwa v37, v247 dst_sel:DWORD dst_unused:UNUSED_PAD src0_sel:WORD_1
	v_rcp_f32_e32 v38, v2
	v_rcp_f32_e32 v39, v41
	v_rcp_f32_e32 v40, v42
	v_rcp_f32_e32 v41, v43
	v_pk_add_f32 v[26:27], v[26:27], v[0:1] op_sel_hi:[1,0]
	v_pk_add_f32 v[28:29], v[28:29], v[0:1] op_sel_hi:[1,0]
	v_pk_mul_f32 v[26:27], v[26:27], v[32:33]
	v_pk_mul_f32 v[28:29], v[28:29], v[36:37]
	v_pk_mul_f32 v[30:31], v[38:39], v[30:31]
	v_pk_mul_f32 v[32:33], v[40:41], v[34:35]
	v_pk_mul_f32 v[26:27], v[26:27], v[30:31]
	v_pk_mul_f32 v[28:29], v[28:29], v[32:33]
	v_cvt_pk_f16_f32 v26, v26, v27
	v_cvt_pk_f16_f32 v27, v28, v29
	global_store_dwordx2 v[20:21], v[26:27], off offset:1696
	s_nop 0
	ds_read_b128 v[30:33], v1 offset:60928
	ds_read_b128 v[34:37], v1 offset:60992
	s_waitcnt lgkmcnt(1)
	v_mfma_f32_16x16x32_f16 v[30:33], v[30:33], v[16:19], 0
	s_waitcnt lgkmcnt(0)
	v_mfma_f32_16x16x32_f16 v[30:33], v[34:37], v[12:15], v[30:33]
	ds_read_b128 v[34:37], v1 offset:61056
	s_waitcnt lgkmcnt(0)
	v_mfma_f32_16x16x32_f16 v[30:33], v[34:37], v[8:11], v[30:33]
	ds_read_b128 v[34:37], v1 offset:61120
	s_waitcnt lgkmcnt(0)
	v_mfma_f32_16x16x32_f16 v[30:33], v[34:37], v[4:7], v[30:33]
	v_cvt_f32_f16_e32 v34, v138
	v_cvt_f32_f16_sdwa v35, v138 dst_sel:DWORD dst_unused:UNUSED_PAD src0_sel:WORD_1
	v_cvt_f32_f16_e32 v28, v139
	v_cvt_f32_f16_sdwa v29, v139 dst_sel:DWORD dst_unused:UNUSED_PAD src0_sel:WORD_1
	v_mul_f32_e32 v2, 0xbfb8aa3b, v34
	v_mul_f32_e32 v38, 0xbfb8aa3b, v35
	v_mul_f32_e32 v39, 0xbfb8aa3b, v28
	v_mul_f32_e32 v40, 0xbfb8aa3b, v29
	v_exp_f32_e32 v2, v2
	v_exp_f32_e32 v38, v38
	v_exp_f32_e32 v39, v39
	v_exp_f32_e32 v40, v40
	v_add_f32_e32 v2, 1.0, v2
	v_add_f32_e32 v41, 1.0, v38
	v_add_f32_e32 v42, 1.0, v39
	v_add_f32_e32 v43, 1.0, v40
	v_cvt_f32_f16_e32 v36, v248
	v_cvt_f32_f16_sdwa v37, v248 dst_sel:DWORD dst_unused:UNUSED_PAD src0_sel:WORD_1
	v_cvt_f32_f16_e32 v26, v249
	v_cvt_f32_f16_sdwa v27, v249 dst_sel:DWORD dst_unused:UNUSED_PAD src0_sel:WORD_1
	v_rcp_f32_e32 v38, v2
	v_rcp_f32_e32 v39, v41
	v_rcp_f32_e32 v40, v42
	v_rcp_f32_e32 v41, v43
	v_pk_add_f32 v[30:31], v[30:31], v[0:1] op_sel_hi:[1,0]
	v_pk_add_f32 v[32:33], v[32:33], v[0:1] op_sel_hi:[1,0]
	v_pk_mul_f32 v[30:31], v[30:31], v[36:37]
	v_pk_mul_f32 v[26:27], v[32:33], v[26:27]
	v_pk_mul_f32 v[32:33], v[38:39], v[34:35]
	v_pk_mul_f32 v[28:29], v[40:41], v[28:29]
	v_pk_mul_f32 v[30:31], v[30:31], v[32:33]
	v_pk_mul_f32 v[26:27], v[26:27], v[28:29]
	v_cvt_pk_f16_f32 v28, v30, v31
	v_cvt_pk_f16_f32 v29, v26, v27
	global_store_dwordx2 v[20:21], v[28:29], off offset:1728
	s_nop 0
	ds_read_b128 v[28:31], v1 offset:65280
	s_waitcnt lgkmcnt(0)
	v_mfma_f32_16x16x32_f16 v[16:19], v[28:31], v[16:19], 0
	ds_read_b128 v[28:31], v1 offset:65344
	s_waitcnt lgkmcnt(0)
	v_mfma_f32_16x16x32_f16 v[12:15], v[28:31], v[12:15], v[16:19]
	s_nop 4
	ds_read_b128 v[16:19], v1 offset:65408
	s_waitcnt lgkmcnt(0)
	v_mfma_f32_16x16x32_f16 v[8:11], v[16:19], v[8:11], v[12:15]
	s_nop 2
	ds_read_b128 v[12:15], v1 offset:65472
	s_waitcnt lgkmcnt(0)
	v_mfma_f32_16x16x32_f16 v[4:7], v[12:15], v[4:7], v[8:11]
	s_nop 1
	v_cvt_f32_f16_e32 v10, v141
	s_nop 3
	v_pk_add_f32 v[4:5], v[4:5], v[0:1] op_sel_hi:[1,0]
	v_pk_add_f32 v[0:1], v[6:7], v[0:1] op_sel_hi:[1,0]
	v_cvt_f32_f16_e32 v6, v140
	v_cvt_f32_f16_sdwa v7, v140 dst_sel:DWORD dst_unused:UNUSED_PAD src0_sel:WORD_1
	v_cvt_f32_f16_sdwa v11, v141 dst_sel:DWORD dst_unused:UNUSED_PAD src0_sel:WORD_1
	v_mul_f32_e32 v15, 0xbfb8aa3b, v10
	v_mul_f32_e32 v2, 0xbfb8aa3b, v6
	v_mul_f32_e32 v14, 0xbfb8aa3b, v7
	v_mul_f32_e32 v16, 0xbfb8aa3b, v11
	v_exp_f32_e32 v2, v2
	v_exp_f32_e32 v14, v14
	v_exp_f32_e32 v15, v15
	v_exp_f32_e32 v16, v16
	v_add_f32_e32 v2, 1.0, v2
	v_add_f32_e32 v17, 1.0, v14
	v_add_f32_e32 v18, 1.0, v15
	v_add_f32_e32 v19, 1.0, v16
	v_cvt_f32_f16_e32 v8, v250
	v_cvt_f32_f16_sdwa v9, v250 dst_sel:DWORD dst_unused:UNUSED_PAD src0_sel:WORD_1
	v_cvt_f32_f16_e32 v12, v251
	v_cvt_f32_f16_sdwa v13, v251 dst_sel:DWORD dst_unused:UNUSED_PAD src0_sel:WORD_1
	v_rcp_f32_e32 v14, v2
	v_rcp_f32_e32 v15, v17
	v_rcp_f32_e32 v16, v18
	v_rcp_f32_e32 v17, v19
	v_pk_mul_f32 v[4:5], v[4:5], v[8:9]
	v_pk_mul_f32 v[0:1], v[0:1], v[12:13]
	v_pk_mul_f32 v[6:7], v[14:15], v[6:7]
	v_pk_mul_f32 v[8:9], v[16:17], v[10:11]
	v_pk_mul_f32 v[4:5], v[4:5], v[6:7]
	v_pk_mul_f32 v[0:1], v[0:1], v[8:9]
	v_cvt_pk_f16_f32 v4, v4, v5
	v_cvt_pk_f16_f32 v5, v0, v1
	global_store_dwordx2 v[20:21], v[4:5], off offset:1760
	s_barrier

.LBB0_863:
	s_or_b64 exec, exec, s[0:1]
	s_cmp_lg_u32 s70, -1
	s_cselect_b32 s0, s70, 0
	s_cselect_b32 s1, s73, 0
	s_waitcnt vmcnt(0)
	v_mov_b32_e32 v0, s0
	v_mov_b32_e32 v1, s1
	s_waitcnt lgkmcnt(0)
	s_barrier
	flat_load_dword v4, v[0:1] sc0 sc1
	s_waitcnt vmcnt(0)
	s_movk_i32 s0, 0x710
	s_waitcnt lgkmcnt(0)
	v_cmp_gt_i32_e32 vcc, s0, v4
	s_mov_b64 s[0:1], -1
	s_and_saveexec_b64 s[92:93], vcc
	s_cbranch_execz .LBB0_858
	s_movk_i32 s0, 0x5f
	v_cmp_lt_i32_e32 vcc, s0, v4
	v_mov_b32_e32 v0, 1
	s_and_saveexec_b64 s[2:3], vcc
	s_movk_i32 s0, 0x510
	v_cmp_gt_u32_e64 s[0:1], s0, v4
	s_nop 1
	v_cndmask_b32_e64 v0, 16, 8, s[0:1]
	s_movk_i32 s0, 0x38f
	v_cmp_lt_u32_e64 s[0:1], s0, v4
	s_nop 1
	v_cndmask_b32_e64 v0, 4, v0, s[0:1]
	s_movk_i32 s0, 0x8f
	v_cmp_lt_u32_e64 s[0:1], s0, v4
	s_nop 1
	v_cndmask_b32_e64 v0, 2, v0, s[0:1]
	s_or_b64 exec, exec, s[2:3]
	v_and_b32_e32 v0, s86, v0
	v_cmp_ne_u32_e64 s[0:1], 0, v0
	s_and_saveexec_b64 s[2:3], s[0:1]
	s_xor_b64 s[94:95], exec, s[2:3]
	s_cbranch_execz .LBB0_1056
	s_and_saveexec_b64 s[0:1], vcc
	s_xor_b64 s[0:1], exec, s[0:1]
	v_writelane_b32 v255, s0, 41
	s_nop 1
	v_writelane_b32 v255, s1, 42
	s_cbranch_execz .LBB0_1013
	s_movk_i32 s0, 0x8f
	v_cmp_lt_u32_e32 vcc, s0, v4
	s_and_saveexec_b64 s[0:1], vcc
	s_xor_b64 s[0:1], exec, s[0:1]
	s_cbranch_execz .LBB0_961
	v_writelane_b32 v255, s0, 31
	s_nop 1
	v_writelane_b32 v255, s1, 32
	s_movk_i32 s0, 0x38f
	v_cmp_lt_u32_e32 vcc, s0, v4
	s_and_saveexec_b64 s[0:1], vcc
	s_xor_b64 s[96:97], exec, s[0:1]
	s_cbranch_execz .LBB0_918
	s_movk_i32 s0, 0x50f
	v_cmp_lt_u32_e32 vcc, s0, v4
	s_and_saveexec_b64 s[0:1], vcc
	s_xor_b64 s[0:1], exec, s[0:1]
	s_cbranch_execz .LBB0_878
	v_and_b32_e32 v5, 3, v4
	v_mov_b32_e32 v8, v238
	s_movk_i32 s2, 0x1000
	v_or_b32_e32 v7, 4, v5
	v_cmp_gt_i32_e32 vcc, s2, v8
	s_and_saveexec_b64 s[2:3], vcc
	s_cbranch_execz .LBB0_874
	v_readlane_b32 s4, v254, 5
	v_lshlrev_b32_e32 v2, 16, v7
	v_readlane_b32 s5, v254, 6
	v_readlane_b32 s18, v254, 19
	v_readlane_b32 s19, v254, 20
	v_lshlrev_b32_e32 v6, 2, v8
	s_mov_b64 s[4:5], 0
	v_lshl_add_u64 v[0:1], s[18:19], 0, v[2:3]
	v_mov_b32_e32 v9, v8
	v_readlane_b32 s6, v254, 7
	v_readlane_b32 s7, v254, 8
	v_readlane_b32 s8, v254, 9
	v_readlane_b32 s9, v254, 10
	v_readlane_b32 s10, v254, 11
	v_readlane_b32 s11, v254, 12
	v_readlane_b32 s12, v254, 13
	v_readlane_b32 s13, v254, 14
	v_readlane_b32 s14, v254, 15
	v_readlane_b32 s15, v254, 16
	v_readlane_b32 s16, v254, 17
	v_readlane_b32 s17, v254, 18
	v_readlane_b32 s52, v255, 24
	v_readlane_b32 s53, v255, 25
	v_readlane_b32 s58, v254, 23
	v_readlane_b32 s59, v254, 24
	v_mov_b32_e32 v244, 0x7fff5e00
	v_lshl_add_u32 v244, v4, 5, v244
	v_and_b32_e32 v244, 0x7fffff80, v244
	v_ashrrev_i32_e32 v245, 6, v8
	v_add_u32_e32 v250, v245, v244
	v_lshlrev_b32_e32 v246, 8, v5
	v_mov_b32_e32 v247, 0
	v_mad_i64_i32 v[248:249], s[54:55], v250, s71, v[246:247]
	v_and_b32_e32 v251, 63, v8
	v_lshlrev_b32_e32 v250, 2, v251
	v_mov_b32_e32 v251, 0
	v_lshl_add_u64 v[248:249], v[248:249], 0, v[250:251]
	v_lshl_add_u64 v[248:249], s[52:53], 0, v[248:249]
	s_mov_b64 s[56:57], 0x1b900
	global_load_dword v210, v[248:249], off
	v_lshl_add_u64 v[248:249], v[248:249], 0, s[56:57]
	global_load_dword v211, v[248:249], off
	v_lshl_add_u64 v[248:249], v[248:249], 0, s[56:57]
	global_load_dword v212, v[248:249], off
	v_lshl_add_u64 v[248:249], v[248:249], 0, s[56:57]
	global_load_dword v213, v[248:249], off
	v_lshl_add_u64 v[248:249], v[248:249], 0, s[56:57]
	global_load_dword v214, v[248:249], off
	v_lshl_add_u64 v[248:249], v[248:249], 0, s[56:57]
	global_load_dword v215, v[248:249], off
	v_lshl_add_u64 v[248:249], v[248:249], 0, s[56:57]
	global_load_dword v216, v[248:249], off
	v_lshl_add_u64 v[248:249], v[248:249], 0, s[56:57]
	global_load_dword v217, v[248:249], off
	v_lshl_add_u64 v[248:249], v[248:249], 0, s[56:57]
	global_load_dword v218, v[248:249], off
	v_lshl_add_u64 v[248:249], v[248:249], 0, s[56:57]
	global_load_dword v219, v[248:249], off
	v_lshl_add_u64 v[248:249], v[248:249], 0, s[56:57]
	global_load_dword v220, v[248:249], off
	v_lshl_add_u64 v[248:249], v[248:249], 0, s[56:57]
	global_load_dword v221, v[248:249], off
	v_lshl_add_u64 v[248:249], v[248:249], 0, s[56:57]
	global_load_dword v222, v[248:249], off
	v_lshl_add_u64 v[248:249], v[248:249], 0, s[56:57]
	global_load_dword v223, v[248:249], off
	v_lshl_add_u64 v[248:249], v[248:249], 0, s[56:57]
	global_load_dword v224, v[248:249], off
	v_lshl_add_u64 v[248:249], v[248:249], 0, s[56:57]
	global_load_dword v225, v[248:249], off
	v_and_b32_e32 v248, 15, v8
	v_lshl_or_b32 v245, v245, 4, v248
	v_add_u32_e32 v244, v245, v244
	v_mov_b64_e32 v[250:251], s[58:59]
	v_mad_i64_i32 v[250:251], s[54:55], v244, s71, v[250:251]
	v_lshl_add_u64 v[250:251], v[250:251], 0, v[246:247]
	v_lshrrev_b32_e32 v246, 1, v8
	v_and_b32_e32 v246, 24, v246
	v_lshl_add_u64 v[250:251], v[250:251], 0, v[246:247]
	s_mov_b64 s[60:61], 0x1000
	v_lshl_add_u64 v[250:251], v[250:251], 0, s[60:61]
	global_load_dwordx2 v[126:127], v[250:251], off offset:2592
	global_load_dwordx2 v[142:143], v[250:251], off offset:544
	global_load_dwordx2 v[128:129], v[250:251], off offset:2624
	global_load_dwordx2 v[144:145], v[250:251], off offset:576
	global_load_dwordx2 v[130:131], v[250:251], off offset:2656
	global_load_dwordx2 v[146:147], v[250:251], off offset:608
	global_load_dwordx2 v[132:133], v[250:251], off offset:2688
	global_load_dwordx2 v[148:149], v[250:251], off offset:640
	global_load_dwordx2 v[134:135], v[250:251], off offset:2720
	global_load_dwordx2 v[244:245], v[250:251], off offset:672
	global_load_dwordx2 v[136:137], v[250:251], off offset:2752
	global_load_dwordx2 v[246:247], v[250:251], off offset:704
	global_load_dwordx2 v[138:139], v[250:251], off offset:2784
	global_load_dwordx2 v[248:249], v[250:251], off offset:736
	global_load_dwordx2 v[140:141], v[250:251], off offset:2816
	global_load_dwordx2 v[250:251], v[250:251], off offset:768
	v_ashrrev_i32_e32 v14, 5, v9
	v_lshlrev_b32_e32 v10, 7, v14
	v_and_b32_e32 v15, 0x7c, v6
	v_ashrrev_i32_e32 v11, 31, v10
	v_lshlrev_b32_e32 v2, 2, v15
	v_lshl_add_u64 v[10:11], v[10:11], 2, v[0:1]
	v_lshl_add_u64 v[10:11], v[10:11], 0, v[2:3]
	s_mov_b64 s[6:7], 0x2000
	global_load_dwordx4 v[178:181], v[10:11], off
	v_lshl_add_u64 v[10:11], v[10:11], 0, s[6:7]
	global_load_dwordx4 v[182:185], v[10:11], off
	v_lshl_add_u64 v[10:11], v[10:11], 0, s[6:7]
	global_load_dwordx4 v[186:189], v[10:11], off
	v_lshl_add_u64 v[10:11], v[10:11], 0, s[6:7]
	global_load_dwordx4 v[190:193], v[10:11], off
	v_lshl_add_u64 v[10:11], v[10:11], 0, s[6:7]
	global_load_dwordx4 v[194:197], v[10:11], off
	v_lshl_add_u64 v[10:11], v[10:11], 0, s[6:7]
	global_load_dwordx4 v[198:201], v[10:11], off
	v_lshl_add_u64 v[10:11], v[10:11], 0, s[6:7]
	global_load_dwordx4 v[202:205], v[10:11], off
	v_lshl_add_u64 v[10:11], v[10:11], 0, s[6:7]
	global_load_dwordx4 v[206:209], v[10:11], off
	v_mul_lo_u32 v14, v14, s48
	v_lshlrev_b32_e32 v15, 1, v15
	v_add3_u32 v2, 0, v14, v15
	s_waitcnt vmcnt(7)
	v_cvt_pk_f16_f32 v178, v178, v179
	v_cvt_pk_f16_f32 v179, v180, v181
	ds_write_b64 v2, v[178:179]
	s_waitcnt vmcnt(6)
	v_cvt_pk_f16_f32 v182, v182, v183
	v_cvt_pk_f16_f32 v183, v184, v185
	ds_write_b64 v2, v[182:183] offset:4352
	s_waitcnt vmcnt(5)
	v_cvt_pk_f16_f32 v186, v186, v187
	v_cvt_pk_f16_f32 v187, v188, v189
	ds_write_b64 v2, v[186:187] offset:8704
	s_waitcnt vmcnt(4)
	v_cvt_pk_f16_f32 v190, v190, v191
	v_cvt_pk_f16_f32 v191, v192, v193
	ds_write_b64 v2, v[190:191] offset:13056
	s_waitcnt vmcnt(3)
	v_cvt_pk_f16_f32 v194, v194, v195
	v_cvt_pk_f16_f32 v195, v196, v197
	ds_write_b64 v2, v[194:195] offset:17408
	s_waitcnt vmcnt(2)
	v_cvt_pk_f16_f32 v198, v198, v199
	v_cvt_pk_f16_f32 v199, v200, v201
	ds_write_b64 v2, v[198:199] offset:21760
	s_waitcnt vmcnt(1)
	v_cvt_pk_f16_f32 v202, v202, v203
	v_cvt_pk_f16_f32 v203, v204, v205
	ds_write_b64 v2, v[202:203] offset:26112
	s_waitcnt vmcnt(0)
	v_cvt_pk_f16_f32 v206, v206, v207
	v_cvt_pk_f16_f32 v207, v208, v209
	ds_write_b64 v2, v[206:207] offset:30464
	s_mov_b64 s[4:5], exec
.LBB0_874:
	s_or_b64 exec, exec, s[2:3]
	v_mov_b32_e32 v0, 0x7fff5e00
	v_lshl_add_u32 v0, v4, 5, v0
	v_ashrrev_i32_e32 v11, 6, v8
	s_movk_i32 s2, 0x80
	v_and_b32_e32 v10, 0x7fffff80, v0
	v_and_b32_e32 v6, 63, v8
	v_cmp_gt_i32_e32 vcc, s2, v11
	v_lshlrev_b32_e32 v9, 7, v5
	s_and_saveexec_b64 s[2:3], vcc
	s_cbranch_execz .LBB0_877
	v_readlane_b32 s4, v254, 5
	v_lshlrev_b32_e32 v2, 2, v9
	v_readlane_b32 s16, v254, 17
	v_readlane_b32 s17, v254, 18
	v_cmp_lt_i32_e32 vcc, v155, v156
	v_lshlrev_b32_e32 v4, 1, v11
	v_lshl_add_u64 v[0:1], s[16:17], 0, v[2:3]
	v_lshlrev_b32_e32 v2, 3, v6
	v_lshl_add_u64 v[0:1], v[0:1], 0, v[2:3]
	global_load_dwordx2 v[0:1], v[0:1], off offset:2048
	v_cndmask_b32_e32 v2, v154, v155, vcc
	v_cmp_lt_i32_e32 vcc, v157, v156
	v_lshlrev_b32_e32 v12, 2, v2
	v_readlane_b32 s4, v255, 26
	v_cndmask_b32_e32 v2, v154, v157, vcc
	v_lshlrev_b32_e32 v13, 2, v2
	v_mul_u32_u24_e32 v2, 0x220, v6
	v_readlane_b32 s5, v254, 6
	v_add3_u32 v14, v2, v4, s4
	v_add_u32_e32 v4, v11, v10
	v_lshlrev_b32_e32 v2, 8, v5
	v_mad_i64_i32 v[4:5], s[4:5], v4, s71, v[2:3]
	v_lshlrev_b32_e32 v2, 2, v6
	v_readlane_b32 s4, v255, 24
	v_lshl_add_u64 v[4:5], v[4:5], 0, v[2:3]
	v_readlane_b32 s5, v255, 25
	v_add_u32_e32 v15, -8, v11
	v_readlane_b32 s6, v254, 7
	v_lshl_add_u64 v[4:5], s[4:5], 0, v[4:5]
	s_mov_b64 s[4:5], 0
	v_readlane_b32 s7, v254, 8
	v_readlane_b32 s8, v254, 9
	v_readlane_b32 s9, v254, 10
	v_readlane_b32 s10, v254, 11
	v_readlane_b32 s11, v254, 12
	v_readlane_b32 s12, v254, 13
	v_readlane_b32 s13, v254, 14
	v_readlane_b32 s14, v254, 15
	v_readlane_b32 s15, v254, 16
	v_readlane_b32 s18, v254, 19
	v_readlane_b32 s19, v254, 20
	v_cvt_f32_f16_sdwa v194, v210 dst_sel:DWORD dst_unused:UNUSED_PAD src0_sel:WORD_1
	v_cvt_f32_f16_e32 v178, v210
	v_cvt_f32_f16_sdwa v195, v211 dst_sel:DWORD dst_unused:UNUSED_PAD src0_sel:WORD_1
	v_cvt_f32_f16_e32 v179, v211
	v_cvt_f32_f16_sdwa v196, v212 dst_sel:DWORD dst_unused:UNUSED_PAD src0_sel:WORD_1
	v_cvt_f32_f16_e32 v180, v212
	v_cvt_f32_f16_sdwa v197, v213 dst_sel:DWORD dst_unused:UNUSED_PAD src0_sel:WORD_1
	v_cvt_f32_f16_e32 v181, v213
	v_cvt_f32_f16_sdwa v198, v214 dst_sel:DWORD dst_unused:UNUSED_PAD src0_sel:WORD_1
	v_cvt_f32_f16_e32 v182, v214
	v_cvt_f32_f16_sdwa v199, v215 dst_sel:DWORD dst_unused:UNUSED_PAD src0_sel:WORD_1
	v_cvt_f32_f16_e32 v183, v215
	v_cvt_f32_f16_sdwa v200, v216 dst_sel:DWORD dst_unused:UNUSED_PAD src0_sel:WORD_1
	v_cvt_f32_f16_e32 v184, v216
	v_cvt_f32_f16_sdwa v201, v217 dst_sel:DWORD dst_unused:UNUSED_PAD src0_sel:WORD_1
	v_cvt_f32_f16_e32 v185, v217
	v_cvt_f32_f16_sdwa v202, v218 dst_sel:DWORD dst_unused:UNUSED_PAD src0_sel:WORD_1
	v_cvt_f32_f16_e32 v186, v218
	v_cvt_f32_f16_sdwa v203, v219 dst_sel:DWORD dst_unused:UNUSED_PAD src0_sel:WORD_1
	v_cvt_f32_f16_e32 v187, v219
	v_cvt_f32_f16_sdwa v204, v220 dst_sel:DWORD dst_unused:UNUSED_PAD src0_sel:WORD_1
	v_cvt_f32_f16_e32 v188, v220
	v_cvt_f32_f16_sdwa v205, v221 dst_sel:DWORD dst_unused:UNUSED_PAD src0_sel:WORD_1
	v_cvt_f32_f16_e32 v189, v221
	v_cvt_f32_f16_sdwa v206, v222 dst_sel:DWORD dst_unused:UNUSED_PAD src0_sel:WORD_1
	v_cvt_f32_f16_e32 v190, v222
	v_cvt_f32_f16_sdwa v207, v223 dst_sel:DWORD dst_unused:UNUSED_PAD src0_sel:WORD_1
	v_cvt_f32_f16_e32 v191, v223
	v_cvt_f32_f16_sdwa v208, v224 dst_sel:DWORD dst_unused:UNUSED_PAD src0_sel:WORD_1
	v_cvt_f32_f16_e32 v192, v224
	v_cvt_f32_f16_sdwa v209, v225 dst_sel:DWORD dst_unused:UNUSED_PAD src0_sel:WORD_1
	v_cvt_f32_f16_e32 v193, v225
	v_mul_f32_e32 v226, v178, v178
	v_mul_f32_e32 v227, v179, v179
	v_mul_f32_e32 v228, v180, v180
	v_mul_f32_e32 v229, v181, v181
	v_mul_f32_e32 v230, v182, v182
	v_mul_f32_e32 v231, v183, v183
	v_mul_f32_e32 v232, v184, v184
	v_mul_f32_e32 v233, v185, v185
	v_mul_f32_e32 v234, v186, v186
	v_mul_f32_e32 v235, v187, v187
	v_mul_f32_e32 v236, v188, v188
	v_mul_f32_e32 v237, v189, v189
	v_mul_f32_e32 v240, v190, v190
	v_mul_f32_e32 v241, v191, v191
	v_mul_f32_e32 v242, v192, v192
	v_mul_f32_e32 v243, v193, v193
	v_mul_f32_e32 v210, v194, v194
	v_mul_f32_e32 v211, v195, v195
	v_mul_f32_e32 v212, v196, v196
	v_mul_f32_e32 v213, v197, v197
	v_mul_f32_e32 v214, v198, v198
	v_mul_f32_e32 v215, v199, v199
	v_mul_f32_e32 v216, v200, v200
	v_mul_f32_e32 v217, v201, v201
	v_mul_f32_e32 v218, v202, v202
	v_mul_f32_e32 v219, v203, v203
	v_mul_f32_e32 v220, v204, v204
	v_mul_f32_e32 v221, v205, v205
	v_mul_f32_e32 v222, v206, v206
	v_mul_f32_e32 v223, v207, v207
	v_mul_f32_e32 v224, v208, v208
	v_mul_f32_e32 v225, v209, v209
	v_add_f32_e32 v210, v226, v210
	v_add_f32_e32 v211, v227, v211
	v_add_f32_e32 v212, v228, v212
	v_add_f32_e32 v213, v229, v213
	v_add_f32_e32 v214, v230, v214
	v_add_f32_e32 v215, v231, v215
	v_add_f32_e32 v216, v232, v216
	v_add_f32_e32 v217, v233, v217
	v_add_f32_e32 v218, v234, v218
	v_add_f32_e32 v219, v235, v219
	v_add_f32_e32 v220, v236, v220
	v_add_f32_e32 v221, v237, v221
	v_add_f32_e32 v222, v240, v222
	v_add_f32_e32 v223, v241, v223
	v_add_f32_e32 v224, v242, v224
	v_add_f32_e32 v225, v243, v225
	v_add_f32_dpp v210, v210, v210 quad_perm:[1,0,3,2] row_mask:0xf bank_mask:0xf bound_ctrl:1
	v_add_f32_dpp v211, v211, v211 quad_perm:[1,0,3,2] row_mask:0xf bank_mask:0xf bound_ctrl:1
	v_add_f32_dpp v212, v212, v212 quad_perm:[1,0,3,2] row_mask:0xf bank_mask:0xf bound_ctrl:1
	v_add_f32_dpp v213, v213, v213 quad_perm:[1,0,3,2] row_mask:0xf bank_mask:0xf bound_ctrl:1
	v_add_f32_dpp v214, v214, v214 quad_perm:[1,0,3,2] row_mask:0xf bank_mask:0xf bound_ctrl:1
	v_add_f32_dpp v215, v215, v215 quad_perm:[1,0,3,2] row_mask:0xf bank_mask:0xf bound_ctrl:1
	v_add_f32_dpp v216, v216, v216 quad_perm:[1,0,3,2] row_mask:0xf bank_mask:0xf bound_ctrl:1
	v_add_f32_dpp v217, v217, v217 quad_perm:[1,0,3,2] row_mask:0xf bank_mask:0xf bound_ctrl:1
	v_add_f32_dpp v218, v218, v218 quad_perm:[1,0,3,2] row_mask:0xf bank_mask:0xf bound_ctrl:1
	v_add_f32_dpp v219, v219, v219 quad_perm:[1,0,3,2] row_mask:0xf bank_mask:0xf bound_ctrl:1
	v_add_f32_dpp v220, v220, v220 quad_perm:[1,0,3,2] row_mask:0xf bank_mask:0xf bound_ctrl:1
	v_add_f32_dpp v221, v221, v221 quad_perm:[1,0,3,2] row_mask:0xf bank_mask:0xf bound_ctrl:1
	v_add_f32_dpp v222, v222, v222 quad_perm:[1,0,3,2] row_mask:0xf bank_mask:0xf bound_ctrl:1
	v_add_f32_dpp v223, v223, v223 quad_perm:[1,0,3,2] row_mask:0xf bank_mask:0xf bound_ctrl:1
	v_add_f32_dpp v224, v224, v224 quad_perm:[1,0,3,2] row_mask:0xf bank_mask:0xf bound_ctrl:1
	v_add_f32_dpp v225, v225, v225 quad_perm:[1,0,3,2] row_mask:0xf bank_mask:0xf bound_ctrl:1
	v_add_f32_dpp v210, v210, v210 quad_perm:[2,3,0,1] row_mask:0xf bank_mask:0xf bound_ctrl:1
	v_add_f32_dpp v211, v211, v211 quad_perm:[2,3,0,1] row_mask:0xf bank_mask:0xf bound_ctrl:1
	v_add_f32_dpp v212, v212, v212 quad_perm:[2,3,0,1] row_mask:0xf bank_mask:0xf bound_ctrl:1
	v_add_f32_dpp v213, v213, v213 quad_perm:[2,3,0,1] row_mask:0xf bank_mask:0xf bound_ctrl:1
	v_add_f32_dpp v214, v214, v214 quad_perm:[2,3,0,1] row_mask:0xf bank_mask:0xf bound_ctrl:1
	v_add_f32_dpp v215, v215, v215 quad_perm:[2,3,0,1] row_mask:0xf bank_mask:0xf bound_ctrl:1
	v_add_f32_dpp v216, v216, v216 quad_perm:[2,3,0,1] row_mask:0xf bank_mask:0xf bound_ctrl:1
	v_add_f32_dpp v217, v217, v217 quad_perm:[2,3,0,1] row_mask:0xf bank_mask:0xf bound_ctrl:1
	v_add_f32_dpp v218, v218, v218 quad_perm:[2,3,0,1] row_mask:0xf bank_mask:0xf bound_ctrl:1
	v_add_f32_dpp v219, v219, v219 quad_perm:[2,3,0,1] row_mask:0xf bank_mask:0xf bound_ctrl:1
	v_add_f32_dpp v220, v220, v220 quad_perm:[2,3,0,1] row_mask:0xf bank_mask:0xf bound_ctrl:1
	v_add_f32_dpp v221, v221, v221 quad_perm:[2,3,0,1] row_mask:0xf bank_mask:0xf bound_ctrl:1
	v_add_f32_dpp v222, v222, v222 quad_perm:[2,3,0,1] row_mask:0xf bank_mask:0xf bound_ctrl:1
	v_add_f32_dpp v223, v223, v223 quad_perm:[2,3,0,1] row_mask:0xf bank_mask:0xf bound_ctrl:1
	v_add_f32_dpp v224, v224, v224 quad_perm:[2,3,0,1] row_mask:0xf bank_mask:0xf bound_ctrl:1
	v_add_f32_dpp v225, v225, v225 quad_perm:[2,3,0,1] row_mask:0xf bank_mask:0xf bound_ctrl:1
	v_add_f32_dpp v210, v210, v210 row_half_mirror row_mask:0xf bank_mask:0xf bound_ctrl:1
	v_add_f32_dpp v211, v211, v211 row_half_mirror row_mask:0xf bank_mask:0xf bound_ctrl:1
	v_add_f32_dpp v212, v212, v212 row_half_mirror row_mask:0xf bank_mask:0xf bound_ctrl:1
	v_add_f32_dpp v213, v213, v213 row_half_mirror row_mask:0xf bank_mask:0xf bound_ctrl:1
	v_add_f32_dpp v214, v214, v214 row_half_mirror row_mask:0xf bank_mask:0xf bound_ctrl:1
	v_add_f32_dpp v215, v215, v215 row_half_mirror row_mask:0xf bank_mask:0xf bound_ctrl:1
	v_add_f32_dpp v216, v216, v216 row_half_mirror row_mask:0xf bank_mask:0xf bound_ctrl:1
	v_add_f32_dpp v217, v217, v217 row_half_mirror row_mask:0xf bank_mask:0xf bound_ctrl:1
	v_add_f32_dpp v218, v218, v218 row_half_mirror row_mask:0xf bank_mask:0xf bound_ctrl:1
	v_add_f32_dpp v219, v219, v219 row_half_mirror row_mask:0xf bank_mask:0xf bound_ctrl:1
	v_add_f32_dpp v220, v220, v220 row_half_mirror row_mask:0xf bank_mask:0xf bound_ctrl:1
	v_add_f32_dpp v221, v221, v221 row_half_mirror row_mask:0xf bank_mask:0xf bound_ctrl:1
	v_add_f32_dpp v222, v222, v222 row_half_mirror row_mask:0xf bank_mask:0xf bound_ctrl:1
	v_add_f32_dpp v223, v223, v223 row_half_mirror row_mask:0xf bank_mask:0xf bound_ctrl:1
	v_add_f32_dpp v224, v224, v224 row_half_mirror row_mask:0xf bank_mask:0xf bound_ctrl:1
	v_add_f32_dpp v225, v225, v225 row_half_mirror row_mask:0xf bank_mask:0xf bound_ctrl:1
	v_add_f32_dpp v210, v210, v210 row_mirror row_mask:0xf bank_mask:0xf bound_ctrl:1
	v_add_f32_dpp v211, v211, v211 row_mirror row_mask:0xf bank_mask:0xf bound_ctrl:1
	v_add_f32_dpp v212, v212, v212 row_mirror row_mask:0xf bank_mask:0xf bound_ctrl:1
	v_add_f32_dpp v213, v213, v213 row_mirror row_mask:0xf bank_mask:0xf bound_ctrl:1
	v_add_f32_dpp v214, v214, v214 row_mirror row_mask:0xf bank_mask:0xf bound_ctrl:1
	v_add_f32_dpp v215, v215, v215 row_mirror row_mask:0xf bank_mask:0xf bound_ctrl:1
	v_add_f32_dpp v216, v216, v216 row_mirror row_mask:0xf bank_mask:0xf bound_ctrl:1
	v_add_f32_dpp v217, v217, v217 row_mirror row_mask:0xf bank_mask:0xf bound_ctrl:1
	v_add_f32_dpp v218, v218, v218 row_mirror row_mask:0xf bank_mask:0xf bound_ctrl:1
	v_add_f32_dpp v219, v219, v219 row_mirror row_mask:0xf bank_mask:0xf bound_ctrl:1
	v_add_f32_dpp v220, v220, v220 row_mirror row_mask:0xf bank_mask:0xf bound_ctrl:1
	v_add_f32_dpp v221, v221, v221 row_mirror row_mask:0xf bank_mask:0xf bound_ctrl:1
	v_add_f32_dpp v222, v222, v222 row_mirror row_mask:0xf bank_mask:0xf bound_ctrl:1
	v_add_f32_dpp v223, v223, v223 row_mirror row_mask:0xf bank_mask:0xf bound_ctrl:1
	v_add_f32_dpp v224, v224, v224 row_mirror row_mask:0xf bank_mask:0xf bound_ctrl:1
	v_add_f32_dpp v225, v225, v225 row_mirror row_mask:0xf bank_mask:0xf bound_ctrl:1
	ds_bpermute_b32 v226, v12, v210
	ds_bpermute_b32 v227, v12, v211
	ds_bpermute_b32 v228, v12, v212
	ds_bpermute_b32 v229, v12, v213
	ds_bpermute_b32 v230, v12, v214
	ds_bpermute_b32 v231, v12, v215
	ds_bpermute_b32 v232, v12, v216
	ds_bpermute_b32 v233, v12, v217
	ds_bpermute_b32 v234, v12, v218
	ds_bpermute_b32 v235, v12, v219
	ds_bpermute_b32 v236, v12, v220
	ds_bpermute_b32 v237, v12, v221
	ds_bpermute_b32 v240, v12, v222
	ds_bpermute_b32 v241, v12, v223
	ds_bpermute_b32 v242, v12, v224
	ds_bpermute_b32 v243, v12, v225
	s_waitcnt lgkmcnt(0)
	v_add_f32_e32 v210, v210, v226
	v_add_f32_e32 v211, v211, v227
	v_add_f32_e32 v212, v212, v228
	v_add_f32_e32 v213, v213, v229
	v_add_f32_e32 v214, v214, v230
	v_add_f32_e32 v215, v215, v231
	v_add_f32_e32 v216, v216, v232
	v_add_f32_e32 v217, v217, v233
	v_add_f32_e32 v218, v218, v234
	v_add_f32_e32 v219, v219, v235
	v_add_f32_e32 v220, v220, v236
	v_add_f32_e32 v221, v221, v237
	v_add_f32_e32 v222, v222, v240
	v_add_f32_e32 v223, v223, v241
	v_add_f32_e32 v224, v224, v242
	v_add_f32_e32 v225, v225, v243
	ds_bpermute_b32 v226, v13, v210
	ds_bpermute_b32 v227, v13, v211
	ds_bpermute_b32 v228, v13, v212
	ds_bpermute_b32 v229, v13, v213
	ds_bpermute_b32 v230, v13, v214
	ds_bpermute_b32 v231, v13, v215
	ds_bpermute_b32 v232, v13, v216
	ds_bpermute_b32 v233, v13, v217
	ds_bpermute_b32 v234, v13, v218
	ds_bpermute_b32 v235, v13, v219
	ds_bpermute_b32 v236, v13, v220
	ds_bpermute_b32 v237, v13, v221
	ds_bpermute_b32 v240, v13, v222
	ds_bpermute_b32 v241, v13, v223
	ds_bpermute_b32 v242, v13, v224
	ds_bpermute_b32 v243, v13, v225
	s_waitcnt lgkmcnt(0)
	v_add_f32_e32 v210, v210, v226
	v_add_f32_e32 v211, v211, v227
	v_add_f32_e32 v212, v212, v228
	v_add_f32_e32 v213, v213, v229
	v_add_f32_e32 v214, v214, v230
	v_add_f32_e32 v215, v215, v231
	v_add_f32_e32 v216, v216, v232
	v_add_f32_e32 v217, v217, v233
	v_add_f32_e32 v218, v218, v234
	v_add_f32_e32 v219, v219, v235
	v_add_f32_e32 v220, v220, v236
	v_add_f32_e32 v221, v221, v237
	v_add_f32_e32 v222, v222, v240
	v_add_f32_e32 v223, v223, v241
	v_add_f32_e32 v224, v224, v242
	v_add_f32_e32 v225, v225, v243
	v_fmamk_f32 v210, v210, 0x3c000000, v158
	v_fmamk_f32 v211, v211, 0x3c000000, v158
	v_fmamk_f32 v212, v212, 0x3c000000, v158
	v_fmamk_f32 v213, v213, 0x3c000000, v158
	v_fmamk_f32 v214, v214, 0x3c000000, v158
	v_fmamk_f32 v215, v215, 0x3c000000, v158
	v_fmamk_f32 v216, v216, 0x3c000000, v158
	v_fmamk_f32 v217, v217, 0x3c000000, v158
	v_fmamk_f32 v218, v218, 0x3c000000, v158
	v_fmamk_f32 v219, v219, 0x3c000000, v158
	v_fmamk_f32 v220, v220, 0x3c000000, v158
	v_fmamk_f32 v221, v221, 0x3c000000, v158
	v_fmamk_f32 v222, v222, 0x3c000000, v158
	v_fmamk_f32 v223, v223, 0x3c000000, v158
	v_fmamk_f32 v224, v224, 0x3c000000, v158
	v_fmamk_f32 v225, v225, 0x3c000000, v158
	v_rsq_f32_e32 v210, v210
	v_rsq_f32_e32 v211, v211
	v_rsq_f32_e32 v212, v212
	v_rsq_f32_e32 v213, v213
	v_rsq_f32_e32 v214, v214
	v_rsq_f32_e32 v215, v215
	v_rsq_f32_e32 v216, v216
	v_rsq_f32_e32 v217, v217
	v_rsq_f32_e32 v218, v218
	v_rsq_f32_e32 v219, v219
	v_rsq_f32_e32 v220, v220
	v_rsq_f32_e32 v221, v221
	v_rsq_f32_e32 v222, v222
	v_rsq_f32_e32 v223, v223
	v_rsq_f32_e32 v224, v224
	v_rsq_f32_e32 v225, v225
	v_mul_f32_e32 v226, v210, v178
	v_mul_f32_e32 v227, v211, v179
	v_mul_f32_e32 v228, v212, v180
	v_mul_f32_e32 v229, v213, v181
	v_mul_f32_e32 v230, v214, v182
	v_mul_f32_e32 v231, v215, v183
	v_mul_f32_e32 v232, v216, v184
	v_mul_f32_e32 v233, v217, v185
	v_mul_f32_e32 v234, v218, v186
	v_mul_f32_e32 v235, v219, v187
	v_mul_f32_e32 v236, v220, v188
	v_mul_f32_e32 v237, v221, v189
	v_mul_f32_e32 v240, v222, v190
	v_mul_f32_e32 v241, v223, v191
	v_mul_f32_e32 v242, v224, v192
	v_mul_f32_e32 v243, v225, v193
	v_mul_f32_e32 v210, v210, v194
	v_mul_f32_e32 v211, v211, v195
	v_mul_f32_e32 v212, v212, v196
	v_mul_f32_e32 v213, v213, v197
	v_mul_f32_e32 v214, v214, v198
	v_mul_f32_e32 v215, v215, v199
	v_mul_f32_e32 v216, v216, v200
	v_mul_f32_e32 v217, v217, v201
	v_mul_f32_e32 v218, v218, v202
	v_mul_f32_e32 v219, v219, v203
	v_mul_f32_e32 v220, v220, v204
	v_mul_f32_e32 v221, v221, v205
	v_mul_f32_e32 v222, v222, v206
	v_mul_f32_e32 v223, v223, v207
	v_mul_f32_e32 v224, v224, v208
	v_mul_f32_e32 v225, v225, v209
	s_waitcnt vmcnt(0)
	v_fma_mixlo_f16 v226, v0, v226, 0
	v_fma_mixlo_f16 v227, v0, v227, 0
	v_fma_mixlo_f16 v228, v0, v228, 0
	v_fma_mixlo_f16 v229, v0, v229, 0
	v_fma_mixlo_f16 v230, v0, v230, 0
	v_fma_mixlo_f16 v231, v0, v231, 0
	v_fma_mixlo_f16 v232, v0, v232, 0
	v_fma_mixlo_f16 v233, v0, v233, 0
	v_fma_mixlo_f16 v234, v0, v234, 0
	v_fma_mixlo_f16 v235, v0, v235, 0
	v_fma_mixlo_f16 v236, v0, v236, 0
	v_fma_mixlo_f16 v237, v0, v237, 0
	v_fma_mixlo_f16 v240, v0, v240, 0
	v_fma_mixlo_f16 v241, v0, v241, 0
	v_fma_mixlo_f16 v242, v0, v242, 0
	v_fma_mixlo_f16 v243, v0, v243, 0
	v_fma_mixlo_f16 v210, v1, v210, 0
	v_fma_mixlo_f16 v211, v1, v211, 0
	v_fma_mixlo_f16 v212, v1, v212, 0
	v_fma_mixlo_f16 v213, v1, v213, 0
	v_fma_mixlo_f16 v214, v1, v214, 0
	v_fma_mixlo_f16 v215, v1, v215, 0
	v_fma_mixlo_f16 v216, v1, v216, 0
	v_fma_mixlo_f16 v217, v1, v217, 0
	v_fma_mixlo_f16 v218, v1, v218, 0
	v_fma_mixlo_f16 v219, v1, v219, 0
	v_fma_mixlo_f16 v220, v1, v220, 0
	v_fma_mixlo_f16 v221, v1, v221, 0
	v_fma_mixlo_f16 v222, v1, v222, 0
	v_fma_mixlo_f16 v223, v1, v223, 0
	v_fma_mixlo_f16 v224, v1, v224, 0
	v_fma_mixlo_f16 v225, v1, v225, 0
	ds_write_b16 v14, v226
	ds_write_b16 v14, v210 offset:272
	ds_write_b16 v14, v227 offset:16
	ds_write_b16 v14, v211 offset:288
	ds_write_b16 v14, v228 offset:32
	ds_write_b16 v14, v212 offset:304
	ds_write_b16 v14, v229 offset:48
	ds_write_b16 v14, v213 offset:320
	ds_write_b16 v14, v230 offset:64
	ds_write_b16 v14, v214 offset:336
	ds_write_b16 v14, v231 offset:80
	ds_write_b16 v14, v215 offset:352
	ds_write_b16 v14, v232 offset:96
	ds_write_b16 v14, v216 offset:368
	ds_write_b16 v14, v233 offset:112
	ds_write_b16 v14, v217 offset:384
	ds_write_b16 v14, v234 offset:128
	ds_write_b16 v14, v218 offset:400
	ds_write_b16 v14, v235 offset:144
	ds_write_b16 v14, v219 offset:416
	ds_write_b16 v14, v236 offset:160
	ds_write_b16 v14, v220 offset:432
	ds_write_b16 v14, v237 offset:176
	ds_write_b16 v14, v221 offset:448
	ds_write_b16 v14, v240 offset:192
	ds_write_b16 v14, v222 offset:464
	ds_write_b16 v14, v241 offset:208
	ds_write_b16 v14, v223 offset:480
	ds_write_b16 v14, v242 offset:224
	ds_write_b16 v14, v224 offset:496
	ds_write_b16 v14, v243 offset:240
	ds_write_b16 v14, v225 offset:512
	s_mov_b64 s[4:5], exec
.LBB0_877:
	s_or_b64 exec, exec, s[2:3]
	v_and_b32_e32 v12, 15, v8
	v_lshl_or_b32 v11, v11, 4, v12
	v_lshrrev_b32_e32 v0, 1, v6
	v_and_b32_e32 v20, 24, v0
	v_lshl_add_u32 v0, v7, 7, v11
	v_readlane_b32 s4, v254, 53
	v_ashrrev_i32_e32 v1, 31, v0
	v_readlane_b32 s5, v254, 54
	v_readlane_b32 s6, v254, 55
	v_readlane_b32 s7, v254, 56
	v_readlane_b32 s8, v254, 57
	v_readlane_b32 s9, v254, 58
	v_readlane_b32 s10, v254, 59
	v_readlane_b32 s11, v254, 60
	v_readlane_b32 s12, v254, 61
	v_readlane_b32 s13, v254, 62
	v_readlane_b32 s14, v254, 63
	v_readlane_b32 s15, v255, 0
	v_readlane_b32 s16, v255, 1
	v_readlane_b32 s17, v255, 2
	v_readlane_b32 s18, v255, 3
	v_readlane_b32 s19, v255, 4
	v_lshl_add_u64 v[0:1], v[0:1], 2, s[4:5]
	v_readlane_b32 s4, v254, 21
	v_readlane_b32 s6, v254, 23
	v_readlane_b32 s7, v254, 24
	v_add_u32_e32 v22, v11, v10
	v_lshlrev_b32_e32 v2, 1, v9
	v_mov_b64_e32 v[4:5], s[6:7]
	v_mad_i64_i32 v[4:5], s[2:3], v22, s71, v[4:5]
	v_lshl_add_u64 v[4:5], v[4:5], 0, v[2:3]
	v_mov_b32_e32 v21, v3
	v_lshl_add_u64 v[24:25], v[4:5], 0, v[20:21]
	s_movk_i32 s2, 0x1000
	v_add_co_u32_e32 v4, vcc, s2, v24
	s_waitcnt lgkmcnt(0)
	s_nop 0
	v_addc_co_u32_e32 v5, vcc, 0, v25, vcc
	s_barrier
	global_load_dword v0, v[0:1], off
	s_nop 0
	v_and_b32_e32 v1, 48, v6
	v_add_u32_e32 v8, 0, v1
	v_mad_u32_u24 v1, v12, s48, v8
	ds_read_b128 v[4:7], v1 offset:34816
	v_mad_u64_u32 v[38:39], s[2:3], v11, s48, v[8:9]
	ds_read_b128 v[16:19], v38
	ds_read_b128 v[26:29], v1 offset:34880
	ds_read_b128 v[12:15], v38 offset:64
	ds_read_b128 v[30:33], v1 offset:34944
	s_waitcnt lgkmcnt(3)
	v_mfma_f32_16x16x32_f16 v[34:37], v[4:7], v[16:19], 0
	ds_read_b128 v[8:11], v38 offset:128
	ds_read_b128 v[4:7], v38 offset:192
	ds_read_b128 v[38:41], v1 offset:35008
	v_ashrrev_i32_e32 v23, 31, v22
	v_readlane_b32 s5, v254, 22
	s_waitcnt lgkmcnt(4)
	v_mfma_f32_16x16x32_f16 v[26:29], v[26:29], v[12:15], v[34:37]
	v_lshlrev_b64 v[22:23], 12, v[22:23]
	v_lshl_add_u64 v[22:23], s[4:5], 0, v[22:23]
	s_mov_b64 s[2:3], 0x1a20
	s_waitcnt lgkmcnt(2)
	v_mfma_f32_16x16x32_f16 v[26:29], v[30:33], v[8:11], v[26:29]
	v_lshl_add_u64 v[30:31], v[22:23], 0, v[2:3]
	v_lshl_add_u64 v[20:21], v[30:31], 0, v[20:21]
	v_lshl_add_u64 v[22:23], v[24:25], 0, s[2:3]
	s_waitcnt lgkmcnt(0)
	v_mfma_f32_16x16x32_f16 v[26:29], v[38:41], v[4:7], v[26:29]
	s_mov_b64 s[2:3], 0x1220
	v_lshl_add_u64 v[24:25], v[24:25], 0, s[2:3]
	v_readlane_b32 s8, v254, 25
	v_readlane_b32 s9, v254, 26
	v_readlane_b32 s10, v254, 27
	v_readlane_b32 s11, v254, 28
	v_readlane_b32 s12, v254, 29
	v_readlane_b32 s13, v254, 30
	v_readlane_b32 s14, v254, 31
	v_readlane_b32 s15, v254, 32
	v_readlane_b32 s16, v254, 33
	v_readlane_b32 s17, v254, 34
	v_readlane_b32 s18, v254, 35
	v_readlane_b32 s19, v254, 36
	s_waitcnt vmcnt(0)
	v_pk_add_f32 v[26:27], v[26:27], v[0:1] op_sel_hi:[1,0]
	v_cvt_f32_f16_e32 v30, v126
	v_cvt_f32_f16_sdwa v31, v126 dst_sel:DWORD dst_unused:UNUSED_PAD src0_sel:WORD_1
	v_cvt_f32_f16_e32 v34, v127
	v_cvt_f32_f16_sdwa v35, v127 dst_sel:DWORD dst_unused:UNUSED_PAD src0_sel:WORD_1
	v_mul_f32_e32 v2, 0xbfb8aa3b, v30
	v_mul_f32_e32 v38, 0xbfb8aa3b, v31
	v_mul_f32_e32 v39, 0xbfb8aa3b, v34
	v_mul_f32_e32 v40, 0xbfb8aa3b, v35
	v_exp_f32_e32 v2, v2
	v_exp_f32_e32 v38, v38
	v_exp_f32_e32 v39, v39
	v_exp_f32_e32 v40, v40
	v_add_f32_e32 v2, 1.0, v2
	v_add_f32_e32 v41, 1.0, v38
	v_add_f32_e32 v42, 1.0, v39
	v_add_f32_e32 v43, 1.0, v40
	v_cvt_f32_f16_e32 v32, v142
	v_cvt_f32_f16_sdwa v33, v142 dst_sel:DWORD dst_unused:UNUSED_PAD src0_sel:WORD_1
	v_cvt_f32_f16_e32 v36, v143
	v_cvt_f32_f16_sdwa v37, v143 dst_sel:DWORD dst_unused:UNUSED_PAD src0_sel:WORD_1
	v_rcp_f32_e32 v38, v2
	v_rcp_f32_e32 v39, v41
	v_rcp_f32_e32 v40, v42
	v_rcp_f32_e32 v41, v43
	v_pk_add_f32 v[28:29], v[28:29], v[0:1] op_sel_hi:[1,0]
	v_pk_mul_f32 v[26:27], v[26:27], v[32:33]
	v_pk_mul_f32 v[28:29], v[28:29], v[36:37]
	v_pk_mul_f32 v[30:31], v[38:39], v[30:31]
	v_pk_mul_f32 v[32:33], v[40:41], v[34:35]
	v_pk_mul_f32 v[26:27], v[26:27], v[30:31]
	v_pk_mul_f32 v[28:29], v[28:29], v[32:33]
	v_cvt_pk_f16_f32 v26, v26, v27
	v_cvt_pk_f16_f32 v27, v28, v29
	global_store_dwordx2 v[20:21], v[26:27], off offset:1536
	ds_read_b128 v[26:29], v1 offset:39168
	ds_read_b128 v[30:33], v1 offset:39232
	s_waitcnt lgkmcnt(1)
	v_mfma_f32_16x16x32_f16 v[26:29], v[26:29], v[16:19], 0
	s_waitcnt lgkmcnt(0)
	v_mfma_f32_16x16x32_f16 v[26:29], v[30:33], v[12:15], v[26:29]
	ds_read_b128 v[30:33], v1 offset:39296
	s_waitcnt lgkmcnt(0)
	v_mfma_f32_16x16x32_f16 v[26:29], v[30:33], v[8:11], v[26:29]
	ds_read_b128 v[30:33], v1 offset:39360
	s_waitcnt lgkmcnt(0)
	v_mfma_f32_16x16x32_f16 v[26:29], v[30:33], v[4:7], v[26:29]
	v_cvt_f32_f16_e32 v30, v128
	v_cvt_f32_f16_sdwa v31, v128 dst_sel:DWORD dst_unused:UNUSED_PAD src0_sel:WORD_1
	v_cvt_f32_f16_e32 v34, v129
	v_cvt_f32_f16_sdwa v35, v129 dst_sel:DWORD dst_unused:UNUSED_PAD src0_sel:WORD_1
	v_mul_f32_e32 v2, 0xbfb8aa3b, v30
	v_mul_f32_e32 v38, 0xbfb8aa3b, v31
	v_mul_f32_e32 v39, 0xbfb8aa3b, v34
	v_mul_f32_e32 v40, 0xbfb8aa3b, v35
	v_exp_f32_e32 v2, v2
	v_exp_f32_e32 v38, v38
	v_exp_f32_e32 v39, v39
	v_exp_f32_e32 v40, v40
	v_add_f32_e32 v2, 1.0, v2
	v_add_f32_e32 v41, 1.0, v38
	v_add_f32_e32 v42, 1.0, v39
	v_add_f32_e32 v43, 1.0, v40
	v_cvt_f32_f16_e32 v32, v144
	v_cvt_f32_f16_sdwa v33, v144 dst_sel:DWORD dst_unused:UNUSED_PAD src0_sel:WORD_1
	v_cvt_f32_f16_e32 v36, v145
	v_cvt_f32_f16_sdwa v37, v145 dst_sel:DWORD dst_unused:UNUSED_PAD src0_sel:WORD_1
	v_rcp_f32_e32 v38, v2
	v_rcp_f32_e32 v39, v41
	v_rcp_f32_e32 v40, v42
	v_rcp_f32_e32 v41, v43
	v_pk_add_f32 v[26:27], v[26:27], v[0:1] op_sel_hi:[1,0]
	v_pk_add_f32 v[28:29], v[28:29], v[0:1] op_sel_hi:[1,0]
	v_pk_mul_f32 v[26:27], v[26:27], v[32:33]
	v_pk_mul_f32 v[28:29], v[28:29], v[36:37]
	v_pk_mul_f32 v[30:31], v[38:39], v[30:31]
	v_pk_mul_f32 v[32:33], v[40:41], v[34:35]
	v_pk_mul_f32 v[26:27], v[26:27], v[30:31]
	v_pk_mul_f32 v[28:29], v[28:29], v[32:33]
	v_cvt_pk_f16_f32 v26, v26, v27
	v_cvt_pk_f16_f32 v27, v28, v29
	global_store_dwordx2 v[20:21], v[26:27], off offset:1568
	ds_read_b128 v[26:29], v1 offset:43520
	ds_read_b128 v[30:33], v1 offset:43584
	s_waitcnt lgkmcnt(1)
	v_mfma_f32_16x16x32_f16 v[26:29], v[26:29], v[16:19], 0
	s_waitcnt lgkmcnt(0)
	v_mfma_f32_16x16x32_f16 v[26:29], v[30:33], v[12:15], v[26:29]
	ds_read_b128 v[30:33], v1 offset:43648
	s_waitcnt lgkmcnt(0)
	v_mfma_f32_16x16x32_f16 v[26:29], v[30:33], v[8:11], v[26:29]
	ds_read_b128 v[30:33], v1 offset:43712
	s_waitcnt lgkmcnt(0)
	v_mfma_f32_16x16x32_f16 v[26:29], v[30:33], v[4:7], v[26:29]
	v_cvt_f32_f16_e32 v30, v130
	v_cvt_f32_f16_sdwa v31, v130 dst_sel:DWORD dst_unused:UNUSED_PAD src0_sel:WORD_1
	v_cvt_f32_f16_e32 v34, v131
	v_cvt_f32_f16_sdwa v35, v131 dst_sel:DWORD dst_unused:UNUSED_PAD src0_sel:WORD_1
	v_mul_f32_e32 v2, 0xbfb8aa3b, v30
	v_mul_f32_e32 v38, 0xbfb8aa3b, v31
	v_mul_f32_e32 v39, 0xbfb8aa3b, v34
	v_mul_f32_e32 v40, 0xbfb8aa3b, v35
	v_exp_f32_e32 v2, v2
	v_exp_f32_e32 v38, v38
	v_exp_f32_e32 v39, v39
	v_exp_f32_e32 v40, v40
	v_add_f32_e32 v2, 1.0, v2
	v_add_f32_e32 v41, 1.0, v38
	v_add_f32_e32 v42, 1.0, v39
	v_add_f32_e32 v43, 1.0, v40
	v_cvt_f32_f16_e32 v32, v146
	v_cvt_f32_f16_sdwa v33, v146 dst_sel:DWORD dst_unused:UNUSED_PAD src0_sel:WORD_1
	v_cvt_f32_f16_e32 v36, v147
	v_cvt_f32_f16_sdwa v37, v147 dst_sel:DWORD dst_unused:UNUSED_PAD src0_sel:WORD_1
	v_rcp_f32_e32 v38, v2
	v_rcp_f32_e32 v39, v41
	v_rcp_f32_e32 v40, v42
	v_rcp_f32_e32 v41, v43
	v_pk_add_f32 v[26:27], v[26:27], v[0:1] op_sel_hi:[1,0]
	v_pk_add_f32 v[28:29], v[28:29], v[0:1] op_sel_hi:[1,0]
	v_pk_mul_f32 v[26:27], v[26:27], v[32:33]
	v_pk_mul_f32 v[28:29], v[28:29], v[36:37]
	v_pk_mul_f32 v[30:31], v[38:39], v[30:31]
	v_pk_mul_f32 v[32:33], v[40:41], v[34:35]
	v_pk_mul_f32 v[26:27], v[26:27], v[30:31]
	v_pk_mul_f32 v[28:29], v[28:29], v[32:33]
	v_cvt_pk_f16_f32 v26, v26, v27
	v_cvt_pk_f16_f32 v27, v28, v29
	global_store_dwordx2 v[20:21], v[26:27], off offset:1600
	ds_read_b128 v[26:29], v1 offset:47872
	ds_read_b128 v[30:33], v1 offset:47936
	s_waitcnt lgkmcnt(1)
	v_mfma_f32_16x16x32_f16 v[26:29], v[26:29], v[16:19], 0
	s_waitcnt lgkmcnt(0)
	v_mfma_f32_16x16x32_f16 v[26:29], v[30:33], v[12:15], v[26:29]
	ds_read_b128 v[30:33], v1 offset:48000
	s_waitcnt lgkmcnt(0)
	v_mfma_f32_16x16x32_f16 v[26:29], v[30:33], v[8:11], v[26:29]
	ds_read_b128 v[30:33], v1 offset:48064
	s_waitcnt lgkmcnt(0)
	v_mfma_f32_16x16x32_f16 v[26:29], v[30:33], v[4:7], v[26:29]
	v_cvt_f32_f16_e32 v30, v132
	v_cvt_f32_f16_sdwa v31, v132 dst_sel:DWORD dst_unused:UNUSED_PAD src0_sel:WORD_1
	v_cvt_f32_f16_e32 v34, v133
	v_cvt_f32_f16_sdwa v35, v133 dst_sel:DWORD dst_unused:UNUSED_PAD src0_sel:WORD_1
	v_mul_f32_e32 v2, 0xbfb8aa3b, v30
	v_mul_f32_e32 v38, 0xbfb8aa3b, v31
	v_mul_f32_e32 v39, 0xbfb8aa3b, v34
	v_mul_f32_e32 v40, 0xbfb8aa3b, v35
	v_exp_f32_e32 v2, v2
	v_exp_f32_e32 v38, v38
	v_exp_f32_e32 v39, v39
	v_exp_f32_e32 v40, v40
	v_add_f32_e32 v2, 1.0, v2
	v_add_f32_e32 v41, 1.0, v38
	v_add_f32_e32 v42, 1.0, v39
	v_add_f32_e32 v43, 1.0, v40
	v_cvt_f32_f16_e32 v32, v148
	v_cvt_f32_f16_sdwa v33, v148 dst_sel:DWORD dst_unused:UNUSED_PAD src0_sel:WORD_1
	v_cvt_f32_f16_e32 v36, v149
	v_cvt_f32_f16_sdwa v37, v149 dst_sel:DWORD dst_unused:UNUSED_PAD src0_sel:WORD_1
	v_rcp_f32_e32 v38, v2
	v_rcp_f32_e32 v39, v41
	v_rcp_f32_e32 v40, v42
	v_rcp_f32_e32 v41, v43
	v_pk_add_f32 v[26:27], v[26:27], v[0:1] op_sel_hi:[1,0]
	v_pk_add_f32 v[28:29], v[28:29], v[0:1] op_sel_hi:[1,0]
	v_pk_mul_f32 v[26:27], v[26:27], v[32:33]
	v_pk_mul_f32 v[28:29], v[28:29], v[36:37]
	v_pk_mul_f32 v[30:31], v[38:39], v[30:31]
	v_pk_mul_f32 v[32:33], v[40:41], v[34:35]
	v_pk_mul_f32 v[26:27], v[26:27], v[30:31]
	v_pk_mul_f32 v[28:29], v[28:29], v[32:33]
	v_cvt_pk_f16_f32 v26, v26, v27
	v_cvt_pk_f16_f32 v27, v28, v29
	global_store_dwordx2 v[20:21], v[26:27], off offset:1632
	ds_read_b128 v[26:29], v1 offset:52224
	ds_read_b128 v[30:33], v1 offset:52288
	s_waitcnt lgkmcnt(1)
	v_mfma_f32_16x16x32_f16 v[26:29], v[26:29], v[16:19], 0
	s_waitcnt lgkmcnt(0)
	v_mfma_f32_16x16x32_f16 v[26:29], v[30:33], v[12:15], v[26:29]
	ds_read_b128 v[30:33], v1 offset:52352
	s_waitcnt lgkmcnt(0)
	v_mfma_f32_16x16x32_f16 v[26:29], v[30:33], v[8:11], v[26:29]
	ds_read_b128 v[30:33], v1 offset:52416
	s_waitcnt lgkmcnt(0)
	v_mfma_f32_16x16x32_f16 v[26:29], v[30:33], v[4:7], v[26:29]
	v_cvt_f32_f16_e32 v30, v134
	v_cvt_f32_f16_sdwa v31, v134 dst_sel:DWORD dst_unused:UNUSED_PAD src0_sel:WORD_1
	v_cvt_f32_f16_e32 v34, v135
	v_cvt_f32_f16_sdwa v35, v135 dst_sel:DWORD dst_unused:UNUSED_PAD src0_sel:WORD_1
	v_mul_f32_e32 v2, 0xbfb8aa3b, v30
	v_mul_f32_e32 v38, 0xbfb8aa3b, v31
	v_mul_f32_e32 v39, 0xbfb8aa3b, v34
	v_mul_f32_e32 v40, 0xbfb8aa3b, v35
	v_exp_f32_e32 v2, v2
	v_exp_f32_e32 v38, v38
	v_exp_f32_e32 v39, v39
	v_exp_f32_e32 v40, v40
	v_add_f32_e32 v2, 1.0, v2
	v_add_f32_e32 v41, 1.0, v38
	v_add_f32_e32 v42, 1.0, v39
	v_add_f32_e32 v43, 1.0, v40
	v_cvt_f32_f16_e32 v32, v244
	v_cvt_f32_f16_sdwa v33, v244 dst_sel:DWORD dst_unused:UNUSED_PAD src0_sel:WORD_1
	v_cvt_f32_f16_e32 v36, v245
	v_cvt_f32_f16_sdwa v37, v245 dst_sel:DWORD dst_unused:UNUSED_PAD src0_sel:WORD_1
	v_rcp_f32_e32 v38, v2
	v_rcp_f32_e32 v39, v41
	v_rcp_f32_e32 v40, v42
	v_rcp_f32_e32 v41, v43
	v_pk_add_f32 v[26:27], v[26:27], v[0:1] op_sel_hi:[1,0]
	v_pk_add_f32 v[28:29], v[28:29], v[0:1] op_sel_hi:[1,0]
	v_pk_mul_f32 v[26:27], v[26:27], v[32:33]
	v_pk_mul_f32 v[28:29], v[28:29], v[36:37]
	v_pk_mul_f32 v[30:31], v[38:39], v[30:31]
	v_pk_mul_f32 v[32:33], v[40:41], v[34:35]
	v_pk_mul_f32 v[26:27], v[26:27], v[30:31]
	v_pk_mul_f32 v[28:29], v[28:29], v[32:33]
	v_cvt_pk_f16_f32 v26, v26, v27
	v_cvt_pk_f16_f32 v27, v28, v29
	global_store_dwordx2 v[20:21], v[26:27], off offset:1664
	ds_read_b128 v[26:29], v1 offset:56576
	ds_read_b128 v[30:33], v1 offset:56640
	s_waitcnt lgkmcnt(1)
	v_mfma_f32_16x16x32_f16 v[26:29], v[26:29], v[16:19], 0
	s_waitcnt lgkmcnt(0)
	v_mfma_f32_16x16x32_f16 v[26:29], v[30:33], v[12:15], v[26:29]
	ds_read_b128 v[30:33], v1 offset:56704
	s_waitcnt lgkmcnt(0)
	v_mfma_f32_16x16x32_f16 v[26:29], v[30:33], v[8:11], v[26:29]
	ds_read_b128 v[30:33], v1 offset:56768
	s_waitcnt lgkmcnt(0)
	v_mfma_f32_16x16x32_f16 v[26:29], v[30:33], v[4:7], v[26:29]
	v_cvt_f32_f16_e32 v30, v136
	v_cvt_f32_f16_sdwa v31, v136 dst_sel:DWORD dst_unused:UNUSED_PAD src0_sel:WORD_1
	v_cvt_f32_f16_e32 v34, v137
	v_cvt_f32_f16_sdwa v35, v137 dst_sel:DWORD dst_unused:UNUSED_PAD src0_sel:WORD_1
	v_mul_f32_e32 v2, 0xbfb8aa3b, v30
	v_mul_f32_e32 v38, 0xbfb8aa3b, v31
	v_mul_f32_e32 v39, 0xbfb8aa3b, v34
	v_mul_f32_e32 v40, 0xbfb8aa3b, v35
	v_exp_f32_e32 v2, v2
	v_exp_f32_e32 v38, v38
	v_exp_f32_e32 v39, v39
	v_exp_f32_e32 v40, v40
	v_add_f32_e32 v2, 1.0, v2
	v_add_f32_e32 v41, 1.0, v38
	v_add_f32_e32 v42, 1.0, v39
	v_add_f32_e32 v43, 1.0, v40
	v_cvt_f32_f16_e32 v32, v246
	v_cvt_f32_f16_sdwa v33, v246 dst_sel:DWORD dst_unused:UNUSED_PAD src0_sel:WORD_1
	v_cvt_f32_f16_e32 v36, v247
	v_cvt_f32_f16_sdwa v37, v247 dst_sel:DWORD dst_unused:UNUSED_PAD src0_sel:WORD_1
	v_rcp_f32_e32 v38, v2
	v_rcp_f32_e32 v39, v41
	v_rcp_f32_e32 v40, v42
	v_rcp_f32_e32 v41, v43
	v_pk_add_f32 v[26:27], v[26:27], v[0:1] op_sel_hi:[1,0]
	v_pk_add_f32 v[28:29], v[28:29], v[0:1] op_sel_hi:[1,0]
	v_pk_mul_f32 v[26:27], v[26:27], v[32:33]
	v_pk_mul_f32 v[28:29], v[28:29], v[36:37]
	v_pk_mul_f32 v[30:31], v[38:39], v[30:31]
	v_pk_mul_f32 v[32:33], v[40:41], v[34:35]
	v_pk_mul_f32 v[26:27], v[26:27], v[30:31]
	v_pk_mul_f32 v[28:29], v[28:29], v[32:33]
	v_cvt_pk_f16_f32 v26, v26, v27
	v_cvt_pk_f16_f32 v27, v28, v29
	global_store_dwordx2 v[20:21], v[26:27], off offset:1696
	s_nop 0
	ds_read_b128 v[30:33], v1 offset:60928
	ds_read_b128 v[34:37], v1 offset:60992
	s_waitcnt lgkmcnt(1)
	v_mfma_f32_16x16x32_f16 v[30:33], v[30:33], v[16:19], 0
	s_waitcnt lgkmcnt(0)
	v_mfma_f32_16x16x32_f16 v[30:33], v[34:37], v[12:15], v[30:33]
	ds_read_b128 v[34:37], v1 offset:61056
	s_waitcnt lgkmcnt(0)
	v_mfma_f32_16x16x32_f16 v[30:33], v[34:37], v[8:11], v[30:33]
	ds_read_b128 v[34:37], v1 offset:61120
	s_waitcnt lgkmcnt(0)
	v_mfma_f32_16x16x32_f16 v[30:33], v[34:37], v[4:7], v[30:33]
	v_cvt_f32_f16_e32 v34, v138
	v_cvt_f32_f16_sdwa v35, v138 dst_sel:DWORD dst_unused:UNUSED_PAD src0_sel:WORD_1
	v_cvt_f32_f16_e32 v28, v139
	v_cvt_f32_f16_sdwa v29, v139 dst_sel:DWORD dst_unused:UNUSED_PAD src0_sel:WORD_1
	v_mul_f32_e32 v2, 0xbfb8aa3b, v34
	v_mul_f32_e32 v38, 0xbfb8aa3b, v35
	v_mul_f32_e32 v39, 0xbfb8aa3b, v28
	v_mul_f32_e32 v40, 0xbfb8aa3b, v29
	v_exp_f32_e32 v2, v2
	v_exp_f32_e32 v38, v38
	v_exp_f32_e32 v39, v39
	v_exp_f32_e32 v40, v40
	v_add_f32_e32 v2, 1.0, v2
	v_add_f32_e32 v41, 1.0, v38
	v_add_f32_e32 v42, 1.0, v39
	v_add_f32_e32 v43, 1.0, v40
	v_cvt_f32_f16_e32 v36, v248
	v_cvt_f32_f16_sdwa v37, v248 dst_sel:DWORD dst_unused:UNUSED_PAD src0_sel:WORD_1
	v_cvt_f32_f16_e32 v26, v249
	v_cvt_f32_f16_sdwa v27, v249 dst_sel:DWORD dst_unused:UNUSED_PAD src0_sel:WORD_1
	v_rcp_f32_e32 v38, v2
	v_rcp_f32_e32 v39, v41
	v_rcp_f32_e32 v40, v42
	v_rcp_f32_e32 v41, v43
	v_pk_add_f32 v[30:31], v[30:31], v[0:1] op_sel_hi:[1,0]
	v_pk_add_f32 v[32:33], v[32:33], v[0:1] op_sel_hi:[1,0]
	v_pk_mul_f32 v[30:31], v[30:31], v[36:37]
	v_pk_mul_f32 v[26:27], v[32:33], v[26:27]
	v_pk_mul_f32 v[32:33], v[38:39], v[34:35]
	v_pk_mul_f32 v[28:29], v[40:41], v[28:29]
	v_pk_mul_f32 v[30:31], v[30:31], v[32:33]
	v_pk_mul_f32 v[26:27], v[26:27], v[28:29]
	v_cvt_pk_f16_f32 v28, v30, v31
	v_cvt_pk_f16_f32 v29, v26, v27
	global_store_dwordx2 v[20:21], v[28:29], off offset:1728
	s_nop 0
	ds_read_b128 v[28:31], v1 offset:65280
	s_waitcnt lgkmcnt(0)
	v_mfma_f32_16x16x32_f16 v[16:19], v[28:31], v[16:19], 0
	ds_read_b128 v[28:31], v1 offset:65344
	s_waitcnt lgkmcnt(0)
	v_mfma_f32_16x16x32_f16 v[12:15], v[28:31], v[12:15], v[16:19]
	s_nop 4
	ds_read_b128 v[16:19], v1 offset:65408
	s_waitcnt lgkmcnt(0)
	v_mfma_f32_16x16x32_f16 v[8:11], v[16:19], v[8:11], v[12:15]
	s_nop 2
	ds_read_b128 v[12:15], v1 offset:65472
	s_waitcnt lgkmcnt(0)
	v_mfma_f32_16x16x32_f16 v[4:7], v[12:15], v[4:7], v[8:11]
	s_nop 1
	v_cvt_f32_f16_e32 v10, v141
	s_nop 3
	v_pk_add_f32 v[4:5], v[4:5], v[0:1] op_sel_hi:[1,0]
	v_pk_add_f32 v[0:1], v[6:7], v[0:1] op_sel_hi:[1,0]
	v_cvt_f32_f16_e32 v6, v140
	v_cvt_f32_f16_sdwa v7, v140 dst_sel:DWORD dst_unused:UNUSED_PAD src0_sel:WORD_1
	v_cvt_f32_f16_sdwa v11, v141 dst_sel:DWORD dst_unused:UNUSED_PAD src0_sel:WORD_1
	v_mul_f32_e32 v15, 0xbfb8aa3b, v10
	v_mul_f32_e32 v2, 0xbfb8aa3b, v6
	v_mul_f32_e32 v14, 0xbfb8aa3b, v7
	v_mul_f32_e32 v16, 0xbfb8aa3b, v11
	v_exp_f32_e32 v2, v2
	v_exp_f32_e32 v14, v14
	v_exp_f32_e32 v15, v15
	v_exp_f32_e32 v16, v16
	v_add_f32_e32 v2, 1.0, v2
	v_add_f32_e32 v17, 1.0, v14
	v_add_f32_e32 v18, 1.0, v15
	v_add_f32_e32 v19, 1.0, v16
	v_cvt_f32_f16_e32 v8, v250
	v_cvt_f32_f16_sdwa v9, v250 dst_sel:DWORD dst_unused:UNUSED_PAD src0_sel:WORD_1
	v_cvt_f32_f16_e32 v12, v251
	v_cvt_f32_f16_sdwa v13, v251 dst_sel:DWORD dst_unused:UNUSED_PAD src0_sel:WORD_1
	v_rcp_f32_e32 v14, v2
	v_rcp_f32_e32 v15, v17
	v_rcp_f32_e32 v16, v18
	v_rcp_f32_e32 v17, v19
	v_pk_mul_f32 v[4:5], v[4:5], v[8:9]
	v_pk_mul_f32 v[0:1], v[0:1], v[12:13]
	v_pk_mul_f32 v[6:7], v[14:15], v[6:7]
	v_pk_mul_f32 v[8:9], v[16:17], v[10:11]
	v_pk_mul_f32 v[4:5], v[4:5], v[6:7]
	v_pk_mul_f32 v[0:1], v[0:1], v[8:9]
	v_cvt_pk_f16_f32 v4, v4, v5
	v_cvt_pk_f16_f32 v5, v0, v1
	global_store_dwordx2 v[20:21], v[4:5], off offset:1760
	s_barrier
